# speedup vs baseline: 1.0266x; 1.0266x over previous
; #define CE(a, b) do { float hi_ = fmaxf(a, b), lo_ = fminf(a, b); a = hi_; b = lo_; } while (0)
; DEVI float pack_key(float v, int idx) { return __uint_as_float((__float_as_uint(v) & ~127u) | (unsigned)(127 - idx)); }
; DEVI void peer_topk_phase(const Params& p, int layer, char* lds) {
;     ...
; #pragma unroll
;       for (int ph = 0; ph < 4; ++ph) {
;         const int tok = w * 8 + (ph >> 1) * 4 + row4, half = ph & 1;
; #pragma unroll
;         for (int m = 0; m < 8; ++m) k[ph][m] = pack_key(SC[(tok * 2 + half) * 136 + i16 + 16 * m], i16 + 16 * m);
;       }
; #pragma unroll
;       for (int ph = 0; ph < 4; ++ph) {
;         CE(k[ph][0], k[ph][1]); CE(k[ph][2], k[ph][3]); CE(k[ph][4], k[ph][5]); CE(k[ph][6], k[ph][7]);
;         CE(k[ph][0], k[ph][2]); CE(k[ph][1], k[ph][3]); CE(k[ph][4], k[ph][6]); CE(k[ph][5], k[ph][7]);
;         CE(k[ph][1], k[ph][2]); CE(k[ph][5], k[ph][6]);
;         CE(k[ph][0], k[ph][4]); CE(k[ph][1], k[ph][5]); CE(k[ph][2], k[ph][6]); CE(k[ph][3], k[ph][7]);
;         CE(k[ph][2], k[ph][4]); CE(k[ph][3], k[ph][5]);
;         CE(k[ph][1], k[ph][2]); CE(k[ph][3], k[ph][4]); CE(k[ph][5], k[ph][6]);
;       }
.LBB0_205:
	s_and_b32 s22, s37, 0xffffffc0
	ds_read2_b32 v[2:3], v159 offset1:16
	s_and_b32 s23, s25, 0x70
	ds_read2_b32 v[4:5], v159 offset0:32 offset1:48
	ds_read2_b32 v[6:7], v159 offset0:64 offset1:80
	v_or_b32_e32 v0, s23, v131
	s_movk_i32 s23, 0xff80
	s_waitcnt lgkmcnt(2)
	v_and_or_b32 v8, v2, s23, v138
	v_and_or_b32 v9, v3, s23, v143
	ds_read2_b32 v[2:3], v159 offset0:96 offset1:112
	s_waitcnt lgkmcnt(2)
	v_and_or_b32 v10, v4, s23, v144
	v_and_or_b32 v11, v5, s23, v145
	v_max_f32_e32 v9, v9, v9
	v_max_f32_e32 v8, v8, v8
	s_waitcnt lgkmcnt(1)
	v_and_or_b32 v12, v6, s23, v146
	ds_read2_b32 v[4:5], v159 offset0:136 offset1:152
	v_and_or_b32 v13, v7, s23, v147
	v_max_f32_e32 v160, v8, v9
	v_min_f32_e32 v8, v8, v9
	v_max_f32_e32 v9, v11, v11
	v_max_f32_e32 v10, v10, v10
	s_waitcnt lgkmcnt(1)
	v_and_or_b32 v14, v2, s23, v148
	v_and_or_b32 v15, v3, s23, v149
	v_max_f32_e32 v11, v10, v9
	v_min_f32_e32 v9, v10, v9
	v_max_f32_e32 v10, v13, v13
	v_max_f32_e32 v12, v12, v12
	v_max_f32_e32 v13, v12, v10
	v_min_f32_e32 v10, v12, v10
	v_max_f32_e32 v12, v15, v15
	v_max_f32_e32 v14, v14, v14
	ds_read2_b32 v[6:7], v159 offset0:168 offset1:184
	v_max_f32_e32 v15, v14, v12
	v_min_f32_e32 v12, v14, v12
	ds_read2_b32 v[2:3], v159 offset0:200 offset1:216
	v_max_f32_e32 v14, v160, v11
	v_min_f32_e32 v11, v160, v11
	v_max_f32_e32 v160, v8, v9
	v_min_f32_e32 v8, v8, v9
	v_max_f32_e32 v9, v13, v15
	v_min_f32_e32 v13, v13, v15
	v_max_f32_e32 v15, v10, v12
	s_waitcnt lgkmcnt(2)
	v_and_or_b32 v16, v4, s23, v138
	v_and_or_b32 v17, v5, s23, v143
	ds_read2_b32 v[4:5], v159 offset0:232 offset1:248
	v_min_f32_e32 v10, v10, v12
	v_max_f32_e32 v12, v160, v11
	v_min_f32_e32 v11, v160, v11
	v_max_f32_e32 v160, v15, v13
	v_min_f32_e32 v13, v15, v13
	v_max_f32_e32 v15, v14, v9
	v_min_f32_e32 v9, v14, v9
	v_max_f32_e32 v14, v12, v160
	v_min_f32_e32 v12, v12, v160
	v_max_f32_e32 v160, v11, v13
	v_min_f32_e32 v11, v11, v13
	v_max_f32_e32 v13, v8, v10
	v_min_f32_e32 v8, v8, v10
	v_max_f32_e32 v10, v160, v9
	v_min_f32_e32 v9, v160, v9
	v_max_f32_e32 v160, v13, v12
	v_min_f32_e32 v12, v13, v12
	s_waitcnt lgkmcnt(2)
	v_and_or_b32 v18, v6, s23, v144
	v_and_or_b32 v19, v7, s23, v145
	v_add_u32_e32 v21, 0x1000, v159
	v_max_f32_e32 v13, v14, v10
	v_min_f32_e32 v10, v14, v10
	v_max_f32_e32 v14, v160, v9
	v_min_f32_e32 v9, v160, v9
	v_max_f32_e32 v160, v12, v11
	v_min_f32_e32 v11, v12, v11
	v_max_f32_e32 v12, v17, v17
	v_max_f32_e32 v16, v16, v16
	s_waitcnt lgkmcnt(1)
	v_and_or_b32 v20, v2, s23, v146
	ds_read2_b32 v[6:7], v21 offset0:64 offset1:80
	v_and_or_b32 v22, v3, s23, v147
	v_max_f32_e32 v17, v16, v12
	v_min_f32_e32 v12, v16, v12
	v_max_f32_e32 v16, v19, v19
	v_max_f32_e32 v18, v18, v18
	s_waitcnt lgkmcnt(1)
	v_and_or_b32 v23, v4, s23, v148
	ds_read2_b32 v[2:3], v21 offset0:96 offset1:112
	v_and_or_b32 v24, v5, s23, v149
	v_max_f32_e32 v19, v18, v16
	v_min_f32_e32 v16, v18, v16
	v_max_f32_e32 v18, v22, v22
	v_max_f32_e32 v20, v20, v20
	v_max_f32_e32 v22, v20, v18
	v_min_f32_e32 v18, v20, v18
	v_max_f32_e32 v20, v24, v24
	v_max_f32_e32 v23, v23, v23
	v_max_f32_e32 v24, v23, v20
	v_min_f32_e32 v20, v23, v20
	ds_read2_b32 v[4:5], v21 offset0:128 offset1:144
	v_max_f32_e32 v23, v17, v19
	v_min_f32_e32 v17, v17, v19
	v_max_f32_e32 v19, v12, v16
	v_min_f32_e32 v12, v12, v16
	v_max_f32_e32 v16, v22, v24
	v_min_f32_e32 v22, v22, v24
	v_max_f32_e32 v24, v18, v20
	s_waitcnt lgkmcnt(2)
	v_and_or_b32 v25, v6, s23, v138
	v_and_or_b32 v26, v7, s23, v143
	ds_read2_b32 v[6:7], v21 offset0:160 offset1:176
	v_min_f32_e32 v18, v18, v20
	v_max_f32_e32 v20, v19, v17
	v_min_f32_e32 v17, v19, v17
	v_max_f32_e32 v19, v24, v22
	v_min_f32_e32 v22, v24, v22
	s_waitcnt lgkmcnt(2)
	v_and_or_b32 v27, v2, s23, v144
	v_and_or_b32 v28, v3, s23, v145
	ds_read2_b32 v[2:3], v21 offset0:200 offset1:216
	v_max_f32_e32 v24, v23, v16
	v_min_f32_e32 v16, v23, v16
	v_max_f32_e32 v23, v20, v19
	v_min_f32_e32 v19, v20, v19
	v_max_f32_e32 v20, v17, v22
	v_min_f32_e32 v17, v17, v22
	v_max_f32_e32 v22, v12, v18
	v_min_f32_e32 v12, v12, v18
	v_max_f32_e32 v18, v20, v16
	v_min_f32_e32 v16, v20, v16
	v_max_f32_e32 v20, v22, v19
	v_min_f32_e32 v19, v22, v19
	v_max_f32_e32 v22, v23, v18
	v_min_f32_e32 v18, v23, v18
	v_max_f32_e32 v23, v20, v16
	v_min_f32_e32 v16, v20, v16
	v_max_f32_e32 v20, v19, v17
	v_min_f32_e32 v17, v19, v17
	v_max_f32_e32 v19, v26, v26
	v_max_f32_e32 v25, v25, v25
	s_waitcnt lgkmcnt(2)
	v_and_or_b32 v29, v4, s23, v146
	v_and_or_b32 v30, v5, s23, v147
	v_max_f32_e32 v26, v25, v19
	v_min_f32_e32 v19, v25, v19
	v_max_f32_e32 v25, v28, v28
	v_max_f32_e32 v27, v27, v27
	s_waitcnt lgkmcnt(1)
	v_and_or_b32 v31, v6, s23, v148
	v_and_or_b32 v32, v7, s23, v149
	v_max_f32_e32 v28, v27, v25
	v_min_f32_e32 v25, v27, v25
	v_max_f32_e32 v27, v30, v30
	v_max_f32_e32 v29, v29, v29
	s_waitcnt lgkmcnt(0)
	v_and_or_b32 v33, v2, s23, v138
	ds_read2_b32 v[4:5], v21 offset0:232 offset1:248
	v_add_u32_e32 v2, 0x1400, v159
	v_max_f32_e32 v30, v29, v27
	v_min_f32_e32 v27, v29, v27
	v_max_f32_e32 v29, v32, v32
	v_max_f32_e32 v31, v31, v31
	ds_read2_b32 v[6:7], v2 offset0:8 offset1:24
	v_max_f32_e32 v32, v31, v29
	v_min_f32_e32 v29, v31, v29
	v_and_or_b32 v21, v3, s23, v143
	ds_read2_b32 v[2:3], v2 offset0:40 offset1:56
	v_max_f32_e32 v31, v26, v28
	v_min_f32_e32 v26, v26, v28
	v_max_f32_e32 v28, v19, v25
	v_min_f32_e32 v19, v19, v25
	v_max_f32_e32 v25, v30, v32
	v_min_f32_e32 v30, v30, v32
	v_max_f32_e32 v32, v27, v29
	v_min_f32_e32 v27, v27, v29
	v_max_f32_e32 v29, v28, v26
	v_min_f32_e32 v26, v28, v26
	v_max_f32_e32 v28, v32, v30
	v_min_f32_e32 v30, v32, v30
	v_max_f32_e32 v32, v31, v25
	v_min_f32_e32 v25, v31, v25
	v_max_f32_e32 v31, v29, v28
	v_min_f32_e32 v28, v29, v28
	v_max_f32_e32 v29, v26, v30
	v_min_f32_e32 v26, v26, v30
	v_max_f32_e32 v30, v19, v27
	s_waitcnt lgkmcnt(2)
; DEVI float row16_max(float v) {
;   v = fmaxf(v, dppf<0xB1, 0xF>(v, v)); v = fmaxf(v, dppf<0x4E, 0xF>(v, v)); v = fmaxf(v, dppf<0x141, 0xF>(v, v)); v = fmaxf(v, dppf<0x140, 0xF>(v, v)); return v;
; }
; template <int N, int M> DEVI void select16m(float (&k)[M][N], float (&res)[M], int i16) {
; #pragma unroll
;   for (int m = 0; m < M; ++m) res[m] = 0.f;
; #pragma unroll
;   for (int kk = 0; kk < 16; ++kk) {
;     float rm[M];
; #pragma unroll
;     for (int m = 0; m < M; ++m) rm[m] = row16_max(k[m][0]);
; #pragma unroll
;     for (int m = 0; m < M; ++m) {
;       const bool win = k[m][0] == rm[m];
; #pragma unroll
;       for (int j = 0; j < N - 1; ++j) k[m][j] = win ? k[m][j + 1] : k[m][j];
;       k[m][N - 1] = win ? -3.0e38f : k[m][N - 1];
;       res[m] = (i16 == kk) ? rm[m] : res[m];
;     }
;   }
; }
	v_and_or_b32 v4, v4, s23, v144
	v_and_or_b32 v5, v5, s23, v145
	v_min_f32_e32 v19, v19, v27
	v_max_f32_e32 v27, v29, v25
	v_min_f32_e32 v25, v29, v25
	v_max_f32_e32 v29, v30, v28
	v_min_f32_e32 v28, v30, v28
	s_waitcnt lgkmcnt(1)
	v_and_or_b32 v6, v6, s23, v146
	v_and_or_b32 v7, v7, s23, v147
	v_max_f32_e32 v30, v31, v27
	v_min_f32_e32 v27, v31, v27
	v_max_f32_e32 v31, v29, v25
	v_min_f32_e32 v25, v29, v25
	v_max_f32_e32 v29, v28, v26
	v_min_f32_e32 v26, v28, v26
	v_max_f32_e32 v21, v21, v21
	v_max_f32_e32 v28, v33, v33
	v_max_f32_e32 v5, v5, v5
	v_max_f32_e32 v4, v4, v4
	s_waitcnt lgkmcnt(0)
	v_and_or_b32 v137, v2, s23, v148
	v_and_or_b32 v3, v3, s23, v149
	v_max_f32_e32 v33, v28, v21
	v_min_f32_e32 v21, v28, v21
	v_max_f32_e32 v28, v4, v5
	v_min_f32_e32 v4, v4, v5
	v_max_f32_e32 v5, v7, v7
	v_max_f32_e32 v6, v6, v6
	v_max_f32_e32 v7, v6, v5
	v_min_f32_e32 v5, v6, v5
	v_max_f32_e32 v3, v3, v3
	v_max_f32_e32 v6, v137, v137
	v_max_f32_e32 v137, v6, v3
	v_min_f32_e32 v3, v6, v3
	v_max_f32_e32 v6, v33, v28
	v_min_f32_e32 v28, v33, v28
	v_max_f32_e32 v33, v21, v4
	v_min_f32_e32 v4, v21, v4
	v_max_f32_e32 v21, v7, v137
	v_min_f32_e32 v7, v7, v137
	v_max_f32_e32 v137, v5, v3
	v_min_f32_e32 v3, v5, v3
	v_max_f32_e32 v5, v33, v28
	v_min_f32_e32 v28, v33, v28
	v_max_f32_e32 v33, v137, v7
	v_min_f32_e32 v7, v137, v7
	v_max_f32_e32 v137, v6, v21
	v_min_f32_e32 v6, v6, v21
	v_max_f32_e32 v21, v5, v33
	v_min_f32_e32 v5, v5, v33
	v_max_f32_e32 v33, v28, v7
	v_min_f32_e32 v7, v28, v7
	v_max_f32_e32 v28, v4, v3
	v_min_f32_e32 v3, v4, v3
	v_max_f32_e32 v4, v33, v6
	v_min_f32_e32 v6, v33, v6
	v_max_f32_e32 v33, v28, v5
	v_min_f32_e32 v5, v28, v5
	v_max_f32_e32 v28, v21, v4
	v_min_f32_e32 v4, v21, v4
	v_max_f32_e32 v21, v33, v6
	v_min_f32_e32 v6, v33, v6
	v_max_f32_e32 v33, v5, v7
	v_min_f32_e32 v5, v5, v7
	v_add_u32_e32 v2, s22, v140
	s_add_i32 s22, 16, 0x11000
	v_max_f32_dpp v7, v15, v15 quad_perm:[1,0,3,2] row_mask:0xf bank_mask:0xf
	s_movk_i32 s37, 0x3fff
	v_lshlrev_b32_e32 v0, 2, v0
	v_max_f32_dpp v7, v7, v7 quad_perm:[2,3,0,1] row_mask:0xf bank_mask:0xf
	s_add_i32 s25, s25, s8
	s_add_i32 s36, s36, s10
	v_max_f32_dpp v7, v7, v7 row_half_mirror row_mask:0xf bank_mask:0xf
	s_nop 1
	v_max_f32_dpp v7, v7, v7 row_mirror row_mask:0xf bank_mask:0xf
	v_cmp_eq_f32_e32 vcc, v15, v7
	v_cndmask_b32_e64 v7, 0, v7, s[38:39]
	v_max_f32_dpp v161, v24, v24 quad_perm:[1,0,3,2] row_mask:0xf bank_mask:0xf
	v_cndmask_b32_e32 v15, v15, v13, vcc
	v_cndmask_b32_e32 v13, v13, v10, vcc
	v_max_f32_dpp v161, v161, v161 quad_perm:[2,3,0,1] row_mask:0xf bank_mask:0xf
	v_cndmask_b32_e32 v10, v10, v14, vcc
	v_cndmask_b32_e32 v14, v14, v9, vcc
	v_max_f32_dpp v161, v161, v161 row_half_mirror row_mask:0xf bank_mask:0xf
	v_cndmask_b32_e32 v9, v9, v160, vcc
	v_cndmask_b32_e32 v160, v160, v11, vcc
	v_max_f32_dpp v161, v161, v161 row_mirror row_mask:0xf bank_mask:0xf
	v_cndmask_b32_e32 v11, v11, v8, vcc
	v_cndmask_b32_e32 v8, v8, v226, vcc
	v_max_f32_dpp v162, v32, v32 quad_perm:[1,0,3,2] row_mask:0xf bank_mask:0xf
	v_cmp_eq_f32_e32 vcc, v24, v161
	v_cndmask_b32_e64 v161, 0, v161, s[38:39]
	v_max_f32_dpp v162, v162, v162 quad_perm:[2,3,0,1] row_mask:0xf bank_mask:0xf
	v_cndmask_b32_e32 v24, v24, v22, vcc
	v_cndmask_b32_e32 v22, v22, v18, vcc
	v_max_f32_dpp v162, v162, v162 row_half_mirror row_mask:0xf bank_mask:0xf
	v_cndmask_b32_e32 v18, v18, v23, vcc
	v_cndmask_b32_e32 v23, v23, v16, vcc
	v_max_f32_dpp v162, v162, v162 row_mirror row_mask:0xf bank_mask:0xf
	v_cndmask_b32_e32 v16, v16, v20, vcc
	v_cndmask_b32_e32 v20, v20, v17, vcc
	v_max_f32_dpp v163, v137, v137 quad_perm:[1,0,3,2] row_mask:0xf bank_mask:0xf
	v_cndmask_b32_e32 v17, v17, v12, vcc
	v_cndmask_b32_e32 v12, v12, v226, vcc
	v_max_f32_dpp v163, v163, v163 quad_perm:[2,3,0,1] row_mask:0xf bank_mask:0xf
	v_cmp_eq_f32_e32 vcc, v32, v162
	v_cndmask_b32_e64 v162, 0, v162, s[38:39]
	v_max_f32_dpp v163, v163, v163 row_half_mirror row_mask:0xf bank_mask:0xf
	v_cndmask_b32_e32 v32, v32, v30, vcc
	v_cndmask_b32_e32 v30, v30, v27, vcc
	v_max_f32_dpp v163, v163, v163 row_mirror row_mask:0xf bank_mask:0xf
	v_cndmask_b32_e32 v27, v27, v31, vcc
	v_cndmask_b32_e32 v31, v31, v25, vcc
	v_max_f32_dpp v164, v15, v15 quad_perm:[1,0,3,2] row_mask:0xf bank_mask:0xf
	v_cndmask_b32_e32 v25, v25, v29, vcc
	v_cndmask_b32_e32 v29, v29, v26, vcc
	v_max_f32_dpp v164, v164, v164 quad_perm:[2,3,0,1] row_mask:0xf bank_mask:0xf
	v_cndmask_b32_e32 v26, v26, v19, vcc
	v_cndmask_b32_e32 v19, v19, v226, vcc
	v_max_f32_dpp v164, v164, v164 row_half_mirror row_mask:0xf bank_mask:0xf
	v_cmp_eq_f32_e32 vcc, v137, v163
	v_cndmask_b32_e64 v163, 0, v163, s[38:39]
	v_max_f32_dpp v164, v164, v164 row_mirror row_mask:0xf bank_mask:0xf
	v_cndmask_b32_e32 v137, v137, v28, vcc
	v_cndmask_b32_e32 v28, v28, v4, vcc
	v_max_f32_dpp v165, v24, v24 quad_perm:[1,0,3,2] row_mask:0xf bank_mask:0xf
	v_cndmask_b32_e32 v4, v4, v21, vcc
	v_cndmask_b32_e32 v21, v21, v6, vcc
	v_max_f32_dpp v165, v165, v165 quad_perm:[2,3,0,1] row_mask:0xf bank_mask:0xf
	v_cndmask_b32_e32 v6, v6, v33, vcc
	v_cndmask_b32_e32 v33, v33, v5, vcc
	v_max_f32_dpp v165, v165, v165 row_half_mirror row_mask:0xf bank_mask:0xf
	v_cndmask_b32_e32 v5, v5, v3, vcc
	v_cndmask_b32_e32 v3, v3, v226, vcc
	v_cmp_eq_f32_e32 vcc, v15, v164
	v_cndmask_b32_e64 v7, v7, v164, s[40:41]
	s_nop 0
	v_cndmask_b32_e32 v15, v15, v13, vcc
	v_max_f32_dpp v165, v165, v165 row_mirror row_mask:0xf bank_mask:0xf
	s_nop 0
	v_max_f32_dpp v164, v15, v15 quad_perm:[1,0,3,2] row_mask:0xf bank_mask:0xf
	v_max_f32_dpp v166, v32, v32 quad_perm:[1,0,3,2] row_mask:0xf bank_mask:0xf
	v_cndmask_b32_e32 v13, v13, v10, vcc
	v_cndmask_b32_e32 v10, v10, v14, vcc
; DEVI float row16_max(float v) {
;   v = fmaxf(v, dppf<0xB1, 0xF>(v, v)); v = fmaxf(v, dppf<0x4E, 0xF>(v, v)); v = fmaxf(v, dppf<0x141, 0xF>(v, v)); v = fmaxf(v, dppf<0x140, 0xF>(v, v)); return v;
; }
; template <int N, int M> DEVI void select16m(float (&k)[M][N], float (&res)[M], int i16) {
; #pragma unroll
;   for (int m = 0; m < M; ++m) res[m] = 0.f;
; #pragma unroll
;   for (int kk = 0; kk < 16; ++kk) {
;     float rm[M];
; #pragma unroll
;     for (int m = 0; m < M; ++m) rm[m] = row16_max(k[m][0]);
; #pragma unroll
;     for (int m = 0; m < M; ++m) {
;       const bool win = k[m][0] == rm[m];
; #pragma unroll
;       for (int j = 0; j < N - 1; ++j) k[m][j] = win ? k[m][j + 1] : k[m][j];
;       k[m][N - 1] = win ? -3.0e38f : k[m][N - 1];
;       res[m] = (i16 == kk) ? rm[m] : res[m];
;     }
;   }
; }
	v_cndmask_b32_e32 v14, v14, v9, vcc
	v_cndmask_b32_e32 v9, v9, v160, vcc
	v_cndmask_b32_e32 v160, v160, v11, vcc
	v_cndmask_b32_e32 v11, v11, v8, vcc
	v_cndmask_b32_e32 v8, v8, v226, vcc
	v_cmp_eq_f32_e32 vcc, v24, v165
	v_cndmask_b32_e64 v161, v161, v165, s[40:41]
	s_nop 0
	v_cndmask_b32_e32 v24, v24, v22, vcc
	v_max_f32_dpp v164, v164, v164 quad_perm:[2,3,0,1] row_mask:0xf bank_mask:0xf
	v_max_f32_dpp v166, v166, v166 quad_perm:[2,3,0,1] row_mask:0xf bank_mask:0xf
	v_cndmask_b32_e32 v22, v22, v18, vcc
	v_max_f32_dpp v164, v164, v164 row_half_mirror row_mask:0xf bank_mask:0xf
	v_max_f32_dpp v166, v166, v166 row_half_mirror row_mask:0xf bank_mask:0xf
	v_cndmask_b32_e32 v18, v18, v23, vcc
	v_max_f32_dpp v164, v164, v164 row_mirror row_mask:0xf bank_mask:0xf
	v_max_f32_dpp v166, v166, v166 row_mirror row_mask:0xf bank_mask:0xf
	v_max_f32_dpp v165, v24, v24 quad_perm:[1,0,3,2] row_mask:0xf bank_mask:0xf
	v_max_f32_dpp v167, v137, v137 quad_perm:[1,0,3,2] row_mask:0xf bank_mask:0xf
	v_cndmask_b32_e32 v23, v23, v16, vcc
	v_cndmask_b32_e32 v16, v16, v20, vcc
	v_cndmask_b32_e32 v20, v20, v17, vcc
	v_cndmask_b32_e32 v17, v17, v12, vcc
	v_cndmask_b32_e32 v12, v12, v226, vcc
	v_cmp_eq_f32_e32 vcc, v32, v166
	v_cndmask_b32_e64 v162, v162, v166, s[40:41]
	s_nop 0
	v_cndmask_b32_e32 v32, v32, v30, vcc
	v_max_f32_dpp v165, v165, v165 quad_perm:[2,3,0,1] row_mask:0xf bank_mask:0xf
	v_max_f32_dpp v167, v167, v167 quad_perm:[2,3,0,1] row_mask:0xf bank_mask:0xf
	v_cndmask_b32_e32 v30, v30, v27, vcc
	v_max_f32_dpp v165, v165, v165 row_half_mirror row_mask:0xf bank_mask:0xf
	v_max_f32_dpp v167, v167, v167 row_half_mirror row_mask:0xf bank_mask:0xf
	v_cndmask_b32_e32 v27, v27, v31, vcc
	v_max_f32_dpp v165, v165, v165 row_mirror row_mask:0xf bank_mask:0xf
	v_max_f32_dpp v167, v167, v167 row_mirror row_mask:0xf bank_mask:0xf
	v_cndmask_b32_e32 v31, v31, v25, vcc
	v_cndmask_b32_e32 v25, v25, v29, vcc
	v_cndmask_b32_e32 v29, v29, v26, vcc
	v_cndmask_b32_e32 v26, v26, v19, vcc
	v_cndmask_b32_e32 v19, v19, v226, vcc
	v_cmp_eq_f32_e32 vcc, v137, v167
	v_max_f32_dpp v166, v32, v32 quad_perm:[1,0,3,2] row_mask:0xf bank_mask:0xf
	s_nop 0
	v_cndmask_b32_e32 v137, v137, v28, vcc
	v_cndmask_b32_e32 v28, v28, v4, vcc
	v_cndmask_b32_e32 v4, v4, v21, vcc
	v_cndmask_b32_e32 v21, v21, v6, vcc
	v_cndmask_b32_e32 v6, v6, v33, vcc
	v_cndmask_b32_e32 v33, v33, v5, vcc
	v_cndmask_b32_e32 v5, v5, v3, vcc
	v_cndmask_b32_e32 v3, v3, v226, vcc
	v_cmp_eq_f32_e32 vcc, v15, v164
	v_cndmask_b32_e64 v163, v163, v167, s[40:41]
	s_nop 0
	v_cndmask_b32_e32 v15, v15, v13, vcc
	v_cndmask_b32_e64 v7, v7, v164, s[42:43]
	v_max_f32_dpp v166, v166, v166 quad_perm:[2,3,0,1] row_mask:0xf bank_mask:0xf
	v_max_f32_dpp v164, v15, v15 quad_perm:[1,0,3,2] row_mask:0xf bank_mask:0xf
	v_cndmask_b32_e32 v13, v13, v10, vcc
	v_cndmask_b32_e32 v10, v10, v14, vcc
	v_cndmask_b32_e32 v14, v14, v9, vcc
	v_cndmask_b32_e32 v9, v9, v160, vcc
	v_cndmask_b32_e32 v160, v160, v11, vcc
	v_cndmask_b32_e32 v11, v11, v8, vcc
	v_cndmask_b32_e32 v8, v8, v226, vcc
	v_cmp_eq_f32_e32 vcc, v24, v165
	v_cndmask_b32_e64 v161, v161, v165, s[42:43]
	v_max_f32_dpp v166, v166, v166 row_half_mirror row_mask:0xf bank_mask:0xf
	v_max_f32_dpp v164, v164, v164 quad_perm:[2,3,0,1] row_mask:0xf bank_mask:0xf
	s_nop 0
	v_max_f32_dpp v166, v166, v166 row_mirror row_mask:0xf bank_mask:0xf
	v_max_f32_dpp v164, v164, v164 row_half_mirror row_mask:0xf bank_mask:0xf
	v_max_f32_dpp v167, v137, v137 quad_perm:[1,0,3,2] row_mask:0xf bank_mask:0xf
	v_cndmask_b32_e32 v24, v24, v22, vcc
	v_max_f32_dpp v164, v164, v164 row_mirror row_mask:0xf bank_mask:0xf
	v_max_f32_dpp v167, v167, v167 quad_perm:[2,3,0,1] row_mask:0xf bank_mask:0xf
	v_max_f32_dpp v165, v24, v24 quad_perm:[1,0,3,2] row_mask:0xf bank_mask:0xf
	v_cndmask_b32_e32 v22, v22, v18, vcc
	v_cndmask_b32_e32 v18, v18, v23, vcc
	v_cndmask_b32_e32 v23, v23, v16, vcc
	v_cndmask_b32_e32 v16, v16, v20, vcc
	v_cndmask_b32_e32 v20, v20, v17, vcc
	v_cndmask_b32_e32 v17, v17, v12, vcc
	v_cndmask_b32_e32 v12, v12, v226, vcc
	v_cmp_eq_f32_e32 vcc, v32, v166
	v_cndmask_b32_e64 v162, v162, v166, s[42:43]
	v_max_f32_dpp v167, v167, v167 row_half_mirror row_mask:0xf bank_mask:0xf
	v_max_f32_dpp v165, v165, v165 quad_perm:[2,3,0,1] row_mask:0xf bank_mask:0xf
	s_nop 0
	v_max_f32_dpp v167, v167, v167 row_mirror row_mask:0xf bank_mask:0xf
	v_cndmask_b32_e32 v32, v32, v30, vcc
	v_cndmask_b32_e32 v30, v30, v27, vcc
	v_cndmask_b32_e32 v27, v27, v31, vcc
	v_cndmask_b32_e32 v31, v31, v25, vcc
	v_cndmask_b32_e32 v25, v25, v29, vcc
	v_cndmask_b32_e32 v29, v29, v26, vcc
	v_cndmask_b32_e32 v26, v26, v19, vcc
	v_cndmask_b32_e32 v19, v19, v226, vcc
	v_cmp_eq_f32_e32 vcc, v137, v167
	v_max_f32_dpp v165, v165, v165 row_half_mirror row_mask:0xf bank_mask:0xf
	s_nop 0
	v_cndmask_b32_e32 v137, v137, v28, vcc
	v_cndmask_b32_e32 v28, v28, v4, vcc
	v_cndmask_b32_e32 v4, v4, v21, vcc
	v_cndmask_b32_e32 v21, v21, v6, vcc
	v_cndmask_b32_e32 v6, v6, v33, vcc
	v_cndmask_b32_e32 v33, v33, v5, vcc
	v_cndmask_b32_e32 v5, v5, v3, vcc
	v_cndmask_b32_e32 v3, v3, v226, vcc
	v_cmp_eq_f32_e32 vcc, v15, v164
	s_nop 1
	v_cndmask_b32_e32 v15, v15, v13, vcc
	v_cndmask_b32_e64 v7, v7, v164, s[44:45]
	v_max_f32_dpp v165, v165, v165 row_mirror row_mask:0xf bank_mask:0xf
	v_max_f32_dpp v164, v15, v15 quad_perm:[1,0,3,2] row_mask:0xf bank_mask:0xf
	v_max_f32_dpp v166, v32, v32 quad_perm:[1,0,3,2] row_mask:0xf bank_mask:0xf
	v_cndmask_b32_e32 v13, v13, v10, vcc
	v_cndmask_b32_e32 v10, v10, v14, vcc
	v_cndmask_b32_e32 v14, v14, v9, vcc
	v_cndmask_b32_e32 v9, v9, v160, vcc
	v_cndmask_b32_e32 v160, v160, v11, vcc
	v_cndmask_b32_e32 v11, v11, v8, vcc
; DEVI float row16_max(float v) {
;   v = fmaxf(v, dppf<0xB1, 0xF>(v, v)); v = fmaxf(v, dppf<0x4E, 0xF>(v, v)); v = fmaxf(v, dppf<0x141, 0xF>(v, v)); v = fmaxf(v, dppf<0x140, 0xF>(v, v)); return v;
; }
; template <int N, int M> DEVI void select16m(float (&k)[M][N], float (&res)[M], int i16) {
; #pragma unroll
;   for (int m = 0; m < M; ++m) res[m] = 0.f;
; #pragma unroll
;   for (int kk = 0; kk < 16; ++kk) {
;     float rm[M];
; #pragma unroll
;     for (int m = 0; m < M; ++m) rm[m] = row16_max(k[m][0]);
; #pragma unroll
;     for (int m = 0; m < M; ++m) {
;       const bool win = k[m][0] == rm[m];
; #pragma unroll
;       for (int j = 0; j < N - 1; ++j) k[m][j] = win ? k[m][j + 1] : k[m][j];
;       k[m][N - 1] = win ? -3.0e38f : k[m][N - 1];
;       res[m] = (i16 == kk) ? rm[m] : res[m];
;     }
;   }
; }
	v_cndmask_b32_e32 v8, v8, v226, vcc
	v_cmp_eq_f32_e32 vcc, v24, v165
	v_cndmask_b32_e64 v161, v161, v165, s[44:45]
	v_cndmask_b32_e64 v163, v163, v167, s[42:43]
	v_max_f32_dpp v164, v164, v164 quad_perm:[2,3,0,1] row_mask:0xf bank_mask:0xf
	v_max_f32_dpp v166, v166, v166 quad_perm:[2,3,0,1] row_mask:0xf bank_mask:0xf
	v_cndmask_b32_e32 v24, v24, v22, vcc
	v_max_f32_dpp v164, v164, v164 row_half_mirror row_mask:0xf bank_mask:0xf
	v_max_f32_dpp v166, v166, v166 row_half_mirror row_mask:0xf bank_mask:0xf
	v_cndmask_b32_e32 v22, v22, v18, vcc
	v_max_f32_dpp v164, v164, v164 row_mirror row_mask:0xf bank_mask:0xf
	v_max_f32_dpp v166, v166, v166 row_mirror row_mask:0xf bank_mask:0xf
	v_max_f32_dpp v165, v24, v24 quad_perm:[1,0,3,2] row_mask:0xf bank_mask:0xf
	v_max_f32_dpp v167, v137, v137 quad_perm:[1,0,3,2] row_mask:0xf bank_mask:0xf
	v_cndmask_b32_e32 v18, v18, v23, vcc
	v_cndmask_b32_e32 v23, v23, v16, vcc
	v_cndmask_b32_e32 v16, v16, v20, vcc
	v_cndmask_b32_e32 v20, v20, v17, vcc
	v_cndmask_b32_e32 v17, v17, v12, vcc
	v_cndmask_b32_e32 v12, v12, v226, vcc
	v_cmp_eq_f32_e32 vcc, v32, v166
	v_cndmask_b32_e64 v162, v162, v166, s[44:45]
	s_nop 0
	v_cndmask_b32_e32 v32, v32, v30, vcc
	v_max_f32_dpp v165, v165, v165 quad_perm:[2,3,0,1] row_mask:0xf bank_mask:0xf
	v_max_f32_dpp v167, v167, v167 quad_perm:[2,3,0,1] row_mask:0xf bank_mask:0xf
	v_cndmask_b32_e32 v30, v30, v27, vcc
	v_max_f32_dpp v165, v165, v165 row_half_mirror row_mask:0xf bank_mask:0xf
	v_max_f32_dpp v167, v167, v167 row_half_mirror row_mask:0xf bank_mask:0xf
	v_cndmask_b32_e32 v27, v27, v31, vcc
	v_max_f32_dpp v165, v165, v165 row_mirror row_mask:0xf bank_mask:0xf
	v_max_f32_dpp v167, v167, v167 row_mirror row_mask:0xf bank_mask:0xf
	v_cndmask_b32_e32 v31, v31, v25, vcc
	v_cndmask_b32_e32 v25, v25, v29, vcc
	v_cndmask_b32_e32 v29, v29, v26, vcc
	v_cndmask_b32_e32 v26, v26, v19, vcc
	v_cndmask_b32_e32 v19, v19, v226, vcc
	v_cmp_eq_f32_e32 vcc, v137, v167
	v_max_f32_dpp v166, v32, v32 quad_perm:[1,0,3,2] row_mask:0xf bank_mask:0xf
	s_nop 0
	v_cndmask_b32_e32 v137, v137, v28, vcc
	v_cndmask_b32_e32 v28, v28, v4, vcc
	v_cndmask_b32_e32 v4, v4, v21, vcc
	v_cndmask_b32_e32 v21, v21, v6, vcc
	v_cndmask_b32_e32 v6, v6, v33, vcc
	v_cndmask_b32_e32 v33, v33, v5, vcc
	v_cndmask_b32_e32 v5, v5, v3, vcc
	v_cndmask_b32_e32 v3, v3, v226, vcc
	v_cmp_eq_f32_e32 vcc, v15, v164
	v_cndmask_b32_e64 v163, v163, v167, s[44:45]
	s_nop 0
	v_cndmask_b32_e32 v15, v15, v13, vcc
	v_cndmask_b32_e64 v7, v7, v164, s[46:47]
	v_max_f32_dpp v166, v166, v166 quad_perm:[2,3,0,1] row_mask:0xf bank_mask:0xf
	v_cndmask_b32_e32 v13, v13, v10, vcc
	v_cndmask_b32_e32 v10, v10, v14, vcc
	v_cndmask_b32_e32 v14, v14, v9, vcc
	v_cndmask_b32_e32 v9, v9, v160, vcc
	v_cndmask_b32_e32 v160, v160, v11, vcc
	v_cndmask_b32_e32 v11, v11, v8, vcc
	v_cndmask_b32_e32 v8, v8, v226, vcc
	v_cmp_eq_f32_e32 vcc, v24, v165
	v_cndmask_b32_e64 v161, v161, v165, s[46:47]
	v_max_f32_e32 v165, v15, v15
	v_max_f32_dpp v164, v15, v165 quad_perm:[1,0,3,2] row_mask:0xf bank_mask:0xf
	v_max_f32_dpp v166, v166, v166 row_half_mirror row_mask:0xf bank_mask:0xf
	s_nop 0
	v_max_f32_dpp v164, v164, v164 quad_perm:[2,3,0,1] row_mask:0xf bank_mask:0xf
	v_max_f32_dpp v166, v166, v166 row_mirror row_mask:0xf bank_mask:0xf
	s_nop 0
	v_max_f32_dpp v164, v164, v164 row_half_mirror row_mask:0xf bank_mask:0xf
	v_max_f32_dpp v167, v137, v137 quad_perm:[1,0,3,2] row_mask:0xf bank_mask:0xf
	v_cndmask_b32_e32 v24, v24, v22, vcc
	v_max_f32_dpp v164, v164, v164 row_mirror row_mask:0xf bank_mask:0xf
	v_max_f32_dpp v167, v167, v167 quad_perm:[2,3,0,1] row_mask:0xf bank_mask:0xf
	v_cndmask_b32_e32 v22, v22, v18, vcc
	v_cndmask_b32_e32 v18, v18, v23, vcc
	v_cndmask_b32_e32 v23, v23, v16, vcc
	v_cndmask_b32_e32 v16, v16, v20, vcc
	v_cndmask_b32_e32 v20, v20, v17, vcc
	v_cndmask_b32_e32 v17, v17, v12, vcc
	v_cndmask_b32_e32 v12, v12, v226, vcc
	v_cmp_eq_f32_e32 vcc, v32, v166
	v_cndmask_b32_e64 v162, v162, v166, s[46:47]
	v_max_f32_e32 v166, v24, v24
	v_max_f32_dpp v165, v24, v166 quad_perm:[1,0,3,2] row_mask:0xf bank_mask:0xf
	v_max_f32_dpp v167, v167, v167 row_half_mirror row_mask:0xf bank_mask:0xf
	s_nop 0
	v_max_f32_dpp v165, v165, v165 quad_perm:[2,3,0,1] row_mask:0xf bank_mask:0xf
	v_max_f32_dpp v167, v167, v167 row_mirror row_mask:0xf bank_mask:0xf
	v_cndmask_b32_e32 v32, v32, v30, vcc
	v_cndmask_b32_e32 v30, v30, v27, vcc
	v_cndmask_b32_e32 v27, v27, v31, vcc
	v_cndmask_b32_e32 v31, v31, v25, vcc
	v_cndmask_b32_e32 v25, v25, v29, vcc
	v_cndmask_b32_e32 v29, v29, v26, vcc
	v_cndmask_b32_e32 v26, v26, v19, vcc
	v_cndmask_b32_e32 v19, v19, v226, vcc
	v_cmp_eq_f32_e32 vcc, v137, v167
	v_max_f32_dpp v165, v165, v165 row_half_mirror row_mask:0xf bank_mask:0xf
	s_nop 0
	v_cndmask_b32_e32 v137, v137, v28, vcc
	v_cndmask_b32_e32 v28, v28, v4, vcc
	v_cndmask_b32_e32 v4, v4, v21, vcc
	v_cndmask_b32_e32 v21, v21, v6, vcc
	v_cndmask_b32_e32 v6, v6, v33, vcc
	v_cndmask_b32_e32 v33, v33, v5, vcc
	v_cndmask_b32_e32 v5, v5, v3, vcc
	v_cndmask_b32_e32 v3, v3, v226, vcc
	v_cmp_eq_f32_e32 vcc, v15, v164
	s_nop 1
	v_cndmask_b32_e32 v15, v15, v13, vcc
	v_cndmask_b32_e64 v7, v7, v164, s[48:49]
	v_max_f32_dpp v165, v165, v165 row_mirror row_mask:0xf bank_mask:0xf
	v_cndmask_b32_e32 v13, v13, v10, vcc
	v_cndmask_b32_e32 v10, v10, v14, vcc
	v_cndmask_b32_e32 v14, v14, v9, vcc
	v_cndmask_b32_e32 v9, v9, v160, vcc
	v_cndmask_b32_e32 v160, v160, v11, vcc
	v_cndmask_b32_e32 v11, v11, v8, vcc
	v_cndmask_b32_e32 v8, v8, v226, vcc
	v_cmp_eq_f32_e32 vcc, v24, v165
	v_cndmask_b32_e64 v161, v161, v165, s[48:49]
	v_max_f32_e32 v165, v15, v15
	v_cndmask_b32_e64 v163, v163, v167, s[46:47]
	v_max_f32_e32 v167, v32, v32
; DEVI float row16_max(float v) {
;   v = fmaxf(v, dppf<0xB1, 0xF>(v, v)); v = fmaxf(v, dppf<0x4E, 0xF>(v, v)); v = fmaxf(v, dppf<0x141, 0xF>(v, v)); v = fmaxf(v, dppf<0x140, 0xF>(v, v)); return v;
; }
; template <int N, int M> DEVI void select16m(float (&k)[M][N], float (&res)[M], int i16) {
; #pragma unroll
;   for (int m = 0; m < M; ++m) res[m] = 0.f;
; #pragma unroll
;   for (int kk = 0; kk < 16; ++kk) {
;     float rm[M];
; #pragma unroll
;     for (int m = 0; m < M; ++m) rm[m] = row16_max(k[m][0]);
; #pragma unroll
;     for (int m = 0; m < M; ++m) {
;       const bool win = k[m][0] == rm[m];
; #pragma unroll
;       for (int j = 0; j < N - 1; ++j) k[m][j] = win ? k[m][j + 1] : k[m][j];
;       k[m][N - 1] = win ? -3.0e38f : k[m][N - 1];
;       res[m] = (i16 == kk) ? rm[m] : res[m];
;     }
;   }
; }
	v_max_f32_dpp v164, v15, v165 quad_perm:[1,0,3,2] row_mask:0xf bank_mask:0xf
	v_max_f32_dpp v166, v32, v167 quad_perm:[1,0,3,2] row_mask:0xf bank_mask:0xf
	v_cndmask_b32_e32 v24, v24, v22, vcc
	v_max_f32_dpp v164, v164, v164 quad_perm:[2,3,0,1] row_mask:0xf bank_mask:0xf
	v_max_f32_dpp v166, v166, v166 quad_perm:[2,3,0,1] row_mask:0xf bank_mask:0xf
	v_cndmask_b32_e32 v22, v22, v18, vcc
	v_max_f32_dpp v164, v164, v164 row_half_mirror row_mask:0xf bank_mask:0xf
	v_max_f32_dpp v166, v166, v166 row_half_mirror row_mask:0xf bank_mask:0xf
	v_cndmask_b32_e32 v18, v18, v23, vcc
	v_max_f32_dpp v164, v164, v164 row_mirror row_mask:0xf bank_mask:0xf
	v_max_f32_dpp v166, v166, v166 row_mirror row_mask:0xf bank_mask:0xf
	v_cndmask_b32_e32 v23, v23, v16, vcc
	v_cndmask_b32_e32 v16, v16, v20, vcc
	v_cndmask_b32_e32 v20, v20, v17, vcc
	v_cndmask_b32_e32 v17, v17, v12, vcc
	v_cndmask_b32_e32 v12, v12, v226, vcc
	v_cmp_eq_f32_e32 vcc, v32, v166
	v_cndmask_b32_e64 v162, v162, v166, s[48:49]
	v_max_f32_e32 v166, v24, v24
	v_max_f32_e32 v168, v137, v137
	v_max_f32_dpp v165, v24, v166 quad_perm:[1,0,3,2] row_mask:0xf bank_mask:0xf
	v_max_f32_dpp v167, v137, v168 quad_perm:[1,0,3,2] row_mask:0xf bank_mask:0xf
	v_cndmask_b32_e32 v32, v32, v30, vcc
	v_max_f32_dpp v165, v165, v165 quad_perm:[2,3,0,1] row_mask:0xf bank_mask:0xf
	v_max_f32_dpp v167, v167, v167 quad_perm:[2,3,0,1] row_mask:0xf bank_mask:0xf
	v_cndmask_b32_e32 v30, v30, v27, vcc
	v_max_f32_dpp v165, v165, v165 row_half_mirror row_mask:0xf bank_mask:0xf
	v_max_f32_dpp v167, v167, v167 row_half_mirror row_mask:0xf bank_mask:0xf
	v_cndmask_b32_e32 v27, v27, v31, vcc
	v_max_f32_dpp v165, v165, v165 row_mirror row_mask:0xf bank_mask:0xf
	v_max_f32_dpp v167, v167, v167 row_mirror row_mask:0xf bank_mask:0xf
	v_cndmask_b32_e32 v31, v31, v25, vcc
	v_cndmask_b32_e32 v25, v25, v29, vcc
	v_cndmask_b32_e32 v29, v29, v26, vcc
	v_cndmask_b32_e32 v26, v26, v19, vcc
	v_cndmask_b32_e32 v19, v19, v226, vcc
	v_cmp_eq_f32_e32 vcc, v137, v167
	v_cndmask_b32_e64 v163, v163, v167, s[48:49]
	v_max_f32_e32 v167, v32, v32
	v_cndmask_b32_e32 v137, v137, v28, vcc
	v_cndmask_b32_e32 v28, v28, v4, vcc
	v_cndmask_b32_e32 v4, v4, v21, vcc
	v_cndmask_b32_e32 v21, v21, v6, vcc
	v_cndmask_b32_e32 v6, v6, v33, vcc
	v_cndmask_b32_e32 v33, v33, v5, vcc
	v_cndmask_b32_e32 v5, v5, v3, vcc
	v_cndmask_b32_e32 v3, v3, v226, vcc
	v_max_f32_dpp v166, v32, v167 quad_perm:[1,0,3,2] row_mask:0xf bank_mask:0xf
	v_cmp_eq_f32_e32 vcc, v15, v164
	v_cndmask_b32_e64 v7, v7, v164, s[50:51]
	s_nop 0
	v_cndmask_b32_e32 v15, v15, v13, vcc
	v_max_f32_dpp v166, v166, v166 quad_perm:[2,3,0,1] row_mask:0xf bank_mask:0xf
	v_cndmask_b32_e32 v13, v13, v10, vcc
	v_cndmask_b32_e32 v10, v10, v14, vcc
	v_cndmask_b32_e32 v14, v14, v9, vcc
	v_cndmask_b32_e32 v9, v9, v160, vcc
	v_cndmask_b32_e32 v160, v160, v11, vcc
	v_cndmask_b32_e32 v11, v11, v8, vcc
	v_cndmask_b32_e32 v8, v8, v226, vcc
	v_cmp_eq_f32_e32 vcc, v24, v165
	v_cndmask_b32_e64 v161, v161, v165, s[50:51]
	v_max_f32_e32 v165, v15, v15
	v_max_f32_dpp v164, v15, v165 quad_perm:[1,0,3,2] row_mask:0xf bank_mask:0xf
	v_max_f32_dpp v166, v166, v166 row_half_mirror row_mask:0xf bank_mask:0xf
	s_nop 0
	v_max_f32_dpp v164, v164, v164 quad_perm:[2,3,0,1] row_mask:0xf bank_mask:0xf
	v_max_f32_dpp v166, v166, v166 row_mirror row_mask:0xf bank_mask:0xf
	s_nop 0
	v_max_f32_dpp v164, v164, v164 row_half_mirror row_mask:0xf bank_mask:0xf
	v_max_f32_e32 v168, v137, v137
	v_max_f32_dpp v167, v137, v168 quad_perm:[1,0,3,2] row_mask:0xf bank_mask:0xf
	v_cndmask_b32_e32 v24, v24, v22, vcc
	v_max_f32_dpp v164, v164, v164 row_mirror row_mask:0xf bank_mask:0xf
	v_max_f32_dpp v167, v167, v167 quad_perm:[2,3,0,1] row_mask:0xf bank_mask:0xf
	v_cndmask_b32_e32 v22, v22, v18, vcc
	v_cndmask_b32_e32 v18, v18, v23, vcc
	v_cndmask_b32_e32 v23, v23, v16, vcc
	v_cndmask_b32_e32 v16, v16, v20, vcc
	v_cndmask_b32_e32 v20, v20, v17, vcc
	v_cndmask_b32_e32 v17, v17, v12, vcc
	v_cndmask_b32_e32 v12, v12, v226, vcc
	v_cmp_eq_f32_e32 vcc, v32, v166
	v_cndmask_b32_e64 v162, v162, v166, s[50:51]
	v_max_f32_e32 v166, v24, v24
	v_max_f32_dpp v165, v24, v166 quad_perm:[1,0,3,2] row_mask:0xf bank_mask:0xf
	v_max_f32_dpp v167, v167, v167 row_half_mirror row_mask:0xf bank_mask:0xf
	s_nop 0
	v_max_f32_dpp v165, v165, v165 quad_perm:[2,3,0,1] row_mask:0xf bank_mask:0xf
	v_max_f32_dpp v167, v167, v167 row_mirror row_mask:0xf bank_mask:0xf
	v_cndmask_b32_e32 v32, v32, v30, vcc
	v_cndmask_b32_e32 v30, v30, v27, vcc
	v_cndmask_b32_e32 v27, v27, v31, vcc
	v_cndmask_b32_e32 v31, v31, v25, vcc
	v_cndmask_b32_e32 v25, v25, v29, vcc
	v_cndmask_b32_e32 v29, v29, v26, vcc
	v_cndmask_b32_e32 v26, v26, v19, vcc
	v_cndmask_b32_e32 v19, v19, v226, vcc
	v_cmp_eq_f32_e32 vcc, v137, v167
	v_max_f32_dpp v165, v165, v165 row_half_mirror row_mask:0xf bank_mask:0xf
	s_nop 0
	v_cndmask_b32_e32 v137, v137, v28, vcc
	v_cndmask_b32_e32 v28, v28, v4, vcc
	v_cndmask_b32_e32 v4, v4, v21, vcc
	v_cndmask_b32_e32 v21, v21, v6, vcc
	v_cndmask_b32_e32 v6, v6, v33, vcc
	v_cndmask_b32_e32 v33, v33, v5, vcc
	v_cndmask_b32_e32 v5, v5, v3, vcc
	v_cndmask_b32_e32 v3, v3, v226, vcc
	v_cmp_eq_f32_e32 vcc, v15, v164
	s_nop 1
	v_cndmask_b32_e32 v15, v15, v13, vcc
	v_cndmask_b32_e64 v7, v7, v164, s[52:53]
	v_max_f32_dpp v165, v165, v165 row_mirror row_mask:0xf bank_mask:0xf
	v_cndmask_b32_e32 v13, v13, v10, vcc
	v_cndmask_b32_e32 v10, v10, v14, vcc
	v_cndmask_b32_e32 v14, v14, v9, vcc
	v_cndmask_b32_e32 v9, v9, v160, vcc
	v_cndmask_b32_e32 v160, v160, v11, vcc
	v_cndmask_b32_e32 v11, v11, v8, vcc
	v_cndmask_b32_e32 v8, v8, v226, vcc
	v_cmp_eq_f32_e32 vcc, v24, v165
	v_cndmask_b32_e64 v161, v161, v165, s[52:53]
; DEVI float row16_max(float v) {
;   v = fmaxf(v, dppf<0xB1, 0xF>(v, v)); v = fmaxf(v, dppf<0x4E, 0xF>(v, v)); v = fmaxf(v, dppf<0x141, 0xF>(v, v)); v = fmaxf(v, dppf<0x140, 0xF>(v, v)); return v;
; }
; template <int N, int M> DEVI void select16m(float (&k)[M][N], float (&res)[M], int i16) {
; #pragma unroll
;   for (int m = 0; m < M; ++m) res[m] = 0.f;
; #pragma unroll
;   for (int kk = 0; kk < 16; ++kk) {
;     float rm[M];
; #pragma unroll
;     for (int m = 0; m < M; ++m) rm[m] = row16_max(k[m][0]);
; #pragma unroll
;     for (int m = 0; m < M; ++m) {
;       const bool win = k[m][0] == rm[m];
; #pragma unroll
;       for (int j = 0; j < N - 1; ++j) k[m][j] = win ? k[m][j + 1] : k[m][j];
;       k[m][N - 1] = win ? -3.0e38f : k[m][N - 1];
;       res[m] = (i16 == kk) ? rm[m] : res[m];
;     }
;   }
; }
	v_max_f32_e32 v165, v15, v15
	v_cndmask_b32_e64 v163, v163, v167, s[50:51]
	v_max_f32_e32 v167, v32, v32
	v_max_f32_dpp v164, v15, v165 quad_perm:[1,0,3,2] row_mask:0xf bank_mask:0xf
	v_max_f32_dpp v166, v32, v167 quad_perm:[1,0,3,2] row_mask:0xf bank_mask:0xf
	v_cndmask_b32_e32 v24, v24, v22, vcc
	v_max_f32_dpp v164, v164, v164 quad_perm:[2,3,0,1] row_mask:0xf bank_mask:0xf
	v_max_f32_dpp v166, v166, v166 quad_perm:[2,3,0,1] row_mask:0xf bank_mask:0xf
	v_cndmask_b32_e32 v22, v22, v18, vcc
	v_max_f32_dpp v164, v164, v164 row_half_mirror row_mask:0xf bank_mask:0xf
	v_max_f32_dpp v166, v166, v166 row_half_mirror row_mask:0xf bank_mask:0xf
	v_cndmask_b32_e32 v18, v18, v23, vcc
	v_max_f32_dpp v164, v164, v164 row_mirror row_mask:0xf bank_mask:0xf
	v_max_f32_dpp v166, v166, v166 row_mirror row_mask:0xf bank_mask:0xf
	v_cndmask_b32_e32 v23, v23, v16, vcc
	v_cndmask_b32_e32 v16, v16, v20, vcc
	v_cndmask_b32_e32 v20, v20, v17, vcc
	v_cndmask_b32_e32 v17, v17, v12, vcc
	v_cndmask_b32_e32 v12, v12, v226, vcc
	v_cmp_eq_f32_e32 vcc, v32, v166
	v_cndmask_b32_e64 v162, v162, v166, s[52:53]
	v_max_f32_e32 v166, v24, v24
	v_max_f32_e32 v168, v137, v137
	v_max_f32_dpp v165, v24, v166 quad_perm:[1,0,3,2] row_mask:0xf bank_mask:0xf
	v_max_f32_dpp v167, v137, v168 quad_perm:[1,0,3,2] row_mask:0xf bank_mask:0xf
	v_cndmask_b32_e32 v32, v32, v30, vcc
	v_max_f32_dpp v165, v165, v165 quad_perm:[2,3,0,1] row_mask:0xf bank_mask:0xf
	v_max_f32_dpp v167, v167, v167 quad_perm:[2,3,0,1] row_mask:0xf bank_mask:0xf
	v_cndmask_b32_e32 v30, v30, v27, vcc
	v_max_f32_dpp v165, v165, v165 row_half_mirror row_mask:0xf bank_mask:0xf
	v_max_f32_dpp v167, v167, v167 row_half_mirror row_mask:0xf bank_mask:0xf
	v_cndmask_b32_e32 v27, v27, v31, vcc
	v_max_f32_dpp v165, v165, v165 row_mirror row_mask:0xf bank_mask:0xf
	v_max_f32_dpp v167, v167, v167 row_mirror row_mask:0xf bank_mask:0xf
	v_cndmask_b32_e32 v31, v31, v25, vcc
	v_cndmask_b32_e32 v25, v25, v29, vcc
	v_cndmask_b32_e32 v29, v29, v26, vcc
	v_cndmask_b32_e32 v26, v26, v19, vcc
	v_cndmask_b32_e32 v19, v19, v226, vcc
	v_cmp_eq_f32_e32 vcc, v137, v167
	v_cndmask_b32_e64 v163, v163, v167, s[52:53]
	v_max_f32_e32 v167, v32, v32
	v_max_f32_dpp v166, v32, v167 quad_perm:[1,0,3,2] row_mask:0xf bank_mask:0xf
	v_cndmask_b32_e32 v137, v137, v28, vcc
	v_max_f32_e32 v168, v137, v137
	v_max_f32_dpp v166, v166, v166 quad_perm:[2,3,0,1] row_mask:0xf bank_mask:0xf
	v_cndmask_b32_e32 v28, v28, v4, vcc
	v_cndmask_b32_e32 v4, v4, v21, vcc
	v_max_f32_dpp v166, v166, v166 row_half_mirror row_mask:0xf bank_mask:0xf
	v_cndmask_b32_e32 v21, v21, v6, vcc
	v_cndmask_b32_e32 v6, v6, v33, vcc
	v_max_f32_dpp v166, v166, v166 row_mirror row_mask:0xf bank_mask:0xf
	v_cndmask_b32_e32 v33, v33, v5, vcc
	v_cndmask_b32_e32 v5, v5, v3, vcc
	v_max_f32_dpp v167, v137, v168 quad_perm:[1,0,3,2] row_mask:0xf bank_mask:0xf
	v_cndmask_b32_e32 v3, v3, v226, vcc
	v_cmp_eq_f32_e32 vcc, v15, v164
	v_max_f32_dpp v167, v167, v167 quad_perm:[2,3,0,1] row_mask:0xf bank_mask:0xf
	s_nop 0
	v_cndmask_b32_e32 v15, v15, v13, vcc
	v_cndmask_b32_e32 v13, v13, v10, vcc
	v_max_f32_dpp v167, v167, v167 row_half_mirror row_mask:0xf bank_mask:0xf
	v_mov_b32_e32 v168, v167
	v_cndmask_b32_e32 v10, v10, v14, vcc
	v_cndmask_b32_e32 v14, v14, v9, vcc
	v_mov_b32_dpp v168, v168 row_mirror row_mask:0xf bank_mask:0xf
	v_max_f32_e32 v168, v168, v168
	v_cndmask_b32_e32 v9, v9, v160, vcc
	v_cndmask_b32_e32 v160, v160, v11, vcc
	v_cndmask_b32_e32 v8, v11, v8, vcc
	v_cmp_eq_f32_e32 vcc, v24, v165
	v_max_f32_e32 v167, v167, v168
	v_cndmask_b32_e64 v7, v7, v164, s[54:55]
	v_cndmask_b32_e32 v11, v24, v22, vcc
	v_cndmask_b32_e32 v22, v22, v18, vcc
	v_cndmask_b32_e32 v18, v18, v23, vcc
	v_cndmask_b32_e32 v23, v23, v16, vcc
	v_cndmask_b32_e32 v16, v16, v20, vcc
	v_cndmask_b32_e32 v20, v20, v17, vcc
	v_cndmask_b32_e32 v12, v17, v12, vcc
	v_cmp_eq_f32_e32 vcc, v32, v166
	v_cndmask_b32_e64 v17, v161, v165, s[54:55]
	v_max_f32_e32 v161, v15, v15
	v_cndmask_b32_e32 v24, v32, v30, vcc
	v_cndmask_b32_e32 v30, v30, v27, vcc
	v_cndmask_b32_e32 v27, v27, v31, vcc
	v_cndmask_b32_e32 v31, v31, v25, vcc
	v_cndmask_b32_e32 v25, v25, v29, vcc
	v_cndmask_b32_e32 v29, v29, v26, vcc
	v_cndmask_b32_e32 v19, v26, v19, vcc
	v_cmp_eq_f32_e32 vcc, v137, v167
	v_cndmask_b32_e64 v26, v162, v166, s[54:55]
	v_max_f32_e32 v162, v11, v11
	v_cndmask_b32_e32 v32, v137, v28, vcc
	v_cndmask_b32_e32 v28, v28, v4, vcc
	v_cndmask_b32_e32 v4, v4, v21, vcc
	v_max_f32_dpp v137, v15, v161 quad_perm:[1,0,3,2] row_mask:0xf bank_mask:0xf
	v_cndmask_b32_e32 v21, v21, v6, vcc
	v_cndmask_b32_e32 v6, v6, v33, vcc
	v_max_f32_dpp v137, v137, v137 quad_perm:[2,3,0,1] row_mask:0xf bank_mask:0xf
	v_cndmask_b32_e32 v33, v33, v5, vcc
	v_cndmask_b32_e32 v3, v5, v3, vcc
	v_max_f32_dpp v137, v137, v137 row_half_mirror row_mask:0xf bank_mask:0xf
	v_cndmask_b32_e64 v5, v163, v167, s[54:55]
	v_max_f32_e32 v163, v24, v24
	v_max_f32_dpp v137, v137, v137 row_mirror row_mask:0xf bank_mask:0xf
	v_max_f32_e32 v164, v32, v32
	v_cmp_eq_f32_e32 vcc, v15, v137
	v_max_f32_dpp v161, v11, v162 quad_perm:[1,0,3,2] row_mask:0xf bank_mask:0xf
	s_nop 0
	v_cndmask_b32_e32 v15, v15, v13, vcc
	v_cndmask_b32_e32 v13, v13, v10, vcc
	v_max_f32_dpp v161, v161, v161 quad_perm:[2,3,0,1] row_mask:0xf bank_mask:0xf
	v_cndmask_b32_e32 v10, v10, v14, vcc
	v_cndmask_b32_e32 v14, v14, v9, vcc
	v_max_f32_dpp v161, v161, v161 row_half_mirror row_mask:0xf bank_mask:0xf
	v_cndmask_b32_e32 v9, v9, v160, vcc
	v_cndmask_b32_e32 v8, v160, v8, vcc
	v_max_f32_dpp v161, v161, v161 row_mirror row_mask:0xf bank_mask:0xf
	v_cmp_eq_f32_e32 vcc, v11, v161
	v_cndmask_b32_e64 v7, v7, v137, s[56:57]
; DEVI float row16_max(float v) {
;   v = fmaxf(v, dppf<0xB1, 0xF>(v, v)); v = fmaxf(v, dppf<0x4E, 0xF>(v, v)); v = fmaxf(v, dppf<0x141, 0xF>(v, v)); v = fmaxf(v, dppf<0x140, 0xF>(v, v)); return v;
; }
; template <int N, int M> DEVI void select16m(float (&k)[M][N], float (&res)[M], int i16) {
; #pragma unroll
;   for (int m = 0; m < M; ++m) res[m] = 0.f;
; #pragma unroll
;   for (int kk = 0; kk < 16; ++kk) {
;     float rm[M];
; #pragma unroll
;     for (int m = 0; m < M; ++m) rm[m] = row16_max(k[m][0]);
; #pragma unroll
;     for (int m = 0; m < M; ++m) {
;       const bool win = k[m][0] == rm[m];
; #pragma unroll
;       for (int j = 0; j < N - 1; ++j) k[m][j] = win ? k[m][j + 1] : k[m][j];
;       k[m][N - 1] = win ? -3.0e38f : k[m][N - 1];
;       res[m] = (i16 == kk) ? rm[m] : res[m];
;     }
;   }
; }
	v_max_f32_dpp v162, v24, v163 quad_perm:[1,0,3,2] row_mask:0xf bank_mask:0xf
	v_cndmask_b32_e32 v11, v11, v22, vcc
	v_cndmask_b32_e32 v22, v22, v18, vcc
	v_max_f32_dpp v162, v162, v162 quad_perm:[2,3,0,1] row_mask:0xf bank_mask:0xf
	v_cndmask_b32_e32 v18, v18, v23, vcc
	v_cndmask_b32_e32 v23, v23, v16, vcc
	v_max_f32_dpp v162, v162, v162 row_half_mirror row_mask:0xf bank_mask:0xf
	v_cndmask_b32_e32 v16, v16, v20, vcc
	v_cndmask_b32_e32 v12, v20, v12, vcc
	v_max_f32_dpp v162, v162, v162 row_mirror row_mask:0xf bank_mask:0xf
	v_cmp_eq_f32_e32 vcc, v24, v162
	v_cndmask_b32_e64 v17, v17, v161, s[56:57]
	v_max_f32_dpp v163, v32, v164 quad_perm:[1,0,3,2] row_mask:0xf bank_mask:0xf
	v_cndmask_b32_e32 v20, v24, v30, vcc
	v_cndmask_b32_e32 v24, v30, v27, vcc
	v_max_f32_dpp v163, v163, v163 quad_perm:[2,3,0,1] row_mask:0xf bank_mask:0xf
	v_cndmask_b32_e32 v27, v27, v31, vcc
	v_cndmask_b32_e32 v30, v31, v25, vcc
	v_max_f32_dpp v163, v163, v163 row_half_mirror row_mask:0xf bank_mask:0xf
	v_mov_b32_e32 v164, v163
	v_cndmask_b32_e32 v25, v25, v29, vcc
	s_nop 0
	v_mov_b32_dpp v164, v164 row_mirror row_mask:0xf bank_mask:0xf
	v_max_f32_e32 v164, v164, v164
	v_max_f32_e32 v163, v163, v164
	v_cndmask_b32_e32 v19, v29, v19, vcc
	v_cmp_eq_f32_e32 vcc, v32, v163
	s_nop 1
	v_cndmask_b32_e32 v29, v32, v28, vcc
	v_max_f32_e32 v32, v15, v15
	v_max_f32_dpp v31, v15, v32 quad_perm:[1,0,3,2] row_mask:0xf bank_mask:0xf
	v_cndmask_b32_e32 v28, v28, v4, vcc
	v_cndmask_b32_e32 v4, v4, v21, vcc
	v_max_f32_dpp v31, v31, v31 quad_perm:[2,3,0,1] row_mask:0xf bank_mask:0xf
	v_cndmask_b32_e32 v21, v21, v6, vcc
	v_cndmask_b32_e32 v6, v6, v33, vcc
	v_max_f32_dpp v31, v31, v31 row_half_mirror row_mask:0xf bank_mask:0xf
	v_cndmask_b32_e32 v3, v33, v3, vcc
	v_max_f32_e32 v33, v11, v11
	v_max_f32_dpp v31, v31, v31 row_mirror row_mask:0xf bank_mask:0xf
	v_max_f32_e32 v137, v20, v20
	v_max_f32_e32 v160, v29, v29
	v_max_f32_dpp v32, v11, v33 quad_perm:[1,0,3,2] row_mask:0xf bank_mask:0xf
	v_cmp_eq_f32_e32 vcc, v15, v31
	v_cndmask_b32_e64 v26, v26, v162, s[56:57]
	v_max_f32_dpp v32, v32, v32 quad_perm:[2,3,0,1] row_mask:0xf bank_mask:0xf
	v_cndmask_b32_e32 v15, v15, v13, vcc
	v_cndmask_b32_e32 v13, v13, v10, vcc
	v_max_f32_dpp v32, v32, v32 row_half_mirror row_mask:0xf bank_mask:0xf
	v_cndmask_b32_e32 v10, v10, v14, vcc
	v_cndmask_b32_e32 v14, v14, v9, vcc
	v_max_f32_dpp v32, v32, v32 row_mirror row_mask:0xf bank_mask:0xf
	v_cndmask_b32_e32 v8, v9, v8, vcc
	v_cmp_eq_f32_e32 vcc, v11, v32
	v_max_f32_dpp v33, v20, v137 quad_perm:[1,0,3,2] row_mask:0xf bank_mask:0xf
	s_nop 0
	v_cndmask_b32_e32 v9, v11, v22, vcc
	v_cndmask_b32_e32 v11, v22, v18, vcc
	v_max_f32_dpp v33, v33, v33 quad_perm:[2,3,0,1] row_mask:0xf bank_mask:0xf
	v_cndmask_b32_e32 v18, v18, v23, vcc
	v_cndmask_b32_e32 v22, v23, v16, vcc
	v_max_f32_dpp v33, v33, v33 row_half_mirror row_mask:0xf bank_mask:0xf
	v_cndmask_b32_e32 v12, v16, v12, vcc
	v_cndmask_b32_e64 v16, v17, v32, s[58:59]
	v_max_f32_dpp v33, v33, v33 row_mirror row_mask:0xf bank_mask:0xf
	v_cmp_eq_f32_e32 vcc, v20, v33
	v_cndmask_b32_e64 v7, v7, v31, s[58:59]
	v_max_f32_dpp v137, v29, v160 quad_perm:[1,0,3,2] row_mask:0xf bank_mask:0xf
	v_cndmask_b32_e32 v17, v20, v24, vcc
	v_cndmask_b32_e32 v20, v24, v27, vcc
	v_max_f32_dpp v137, v137, v137 quad_perm:[2,3,0,1] row_mask:0xf bank_mask:0xf
	v_cndmask_b32_e32 v23, v27, v30, vcc
	v_cndmask_b32_e32 v24, v30, v25, vcc
	v_max_f32_dpp v137, v137, v137 row_half_mirror row_mask:0xf bank_mask:0xf
	v_mov_b32_e32 v160, v137
	v_cndmask_b32_e32 v19, v25, v19, vcc
	v_cndmask_b32_e64 v25, v26, v33, s[58:59]
	v_mov_b32_dpp v160, v160 row_mirror row_mask:0xf bank_mask:0xf
	v_max_f32_e32 v160, v160, v160
	v_max_f32_e32 v137, v137, v160
	v_cmp_eq_f32_e32 vcc, v29, v137
	v_max_f32_e32 v30, v17, v17
	v_cndmask_b32_e64 v5, v5, v163, s[56:57]
	v_cndmask_b32_e32 v27, v28, v4, vcc
	v_cndmask_b32_e32 v4, v4, v21, vcc
	v_cndmask_b32_e32 v21, v21, v6, vcc
	v_cndmask_b32_e32 v3, v6, v3, vcc
	v_cndmask_b32_e32 v26, v29, v28, vcc
	v_max_f32_e32 v28, v15, v15
	v_max_f32_dpp v6, v15, v28 quad_perm:[1,0,3,2] row_mask:0xf bank_mask:0xf
	v_max_f32_e32 v29, v9, v9
	v_max_f32_e32 v31, v26, v26
	v_max_f32_dpp v6, v6, v6 quad_perm:[2,3,0,1] row_mask:0xf bank_mask:0xf
	v_cndmask_b32_e64 v5, v5, v137, s[58:59]
	s_nop 0
	v_max_f32_dpp v6, v6, v6 row_half_mirror row_mask:0xf bank_mask:0xf
	s_nop 1
	v_max_f32_dpp v6, v6, v6 row_mirror row_mask:0xf bank_mask:0xf
	v_cmp_eq_f32_e32 vcc, v15, v6
	v_cndmask_b32_e64 v6, v7, v6, s[16:17]
	v_max_f32_dpp v28, v9, v29 quad_perm:[1,0,3,2] row_mask:0xf bank_mask:0xf
	v_cndmask_b32_e32 v15, v15, v13, vcc
	v_cndmask_b32_e32 v13, v13, v10, vcc
	v_max_f32_dpp v28, v28, v28 quad_perm:[2,3,0,1] row_mask:0xf bank_mask:0xf
	v_cndmask_b32_e32 v10, v10, v14, vcc
	v_cndmask_b32_e32 v8, v14, v8, vcc
	v_max_f32_dpp v28, v28, v28 row_half_mirror row_mask:0xf bank_mask:0xf
	s_nop 1
	v_max_f32_dpp v28, v28, v28 row_mirror row_mask:0xf bank_mask:0xf
	v_cmp_eq_f32_e32 vcc, v9, v28
	v_cndmask_b32_e64 v14, v16, v28, s[16:17]
	v_max_f32_dpp v29, v17, v30 quad_perm:[1,0,3,2] row_mask:0xf bank_mask:0xf
	v_cndmask_b32_e32 v7, v9, v11, vcc
	v_cndmask_b32_e32 v9, v11, v18, vcc
	v_max_f32_dpp v29, v29, v29 quad_perm:[2,3,0,1] row_mask:0xf bank_mask:0xf
	v_cndmask_b32_e32 v11, v18, v22, vcc
	v_cndmask_b32_e32 v12, v22, v12, vcc
	v_max_f32_dpp v29, v29, v29 row_half_mirror row_mask:0xf bank_mask:0xf
	s_nop 1
	v_max_f32_dpp v29, v29, v29 row_mirror row_mask:0xf bank_mask:0xf
	v_cmp_eq_f32_e32 vcc, v17, v29
	s_nop 0
	v_max_f32_dpp v30, v26, v31 quad_perm:[1,0,3,2] row_mask:0xf bank_mask:0xf
	v_cndmask_b32_e32 v16, v17, v20, vcc
; DEVI float row16_max(float v) {
;   v = fmaxf(v, dppf<0xB1, 0xF>(v, v)); v = fmaxf(v, dppf<0x4E, 0xF>(v, v)); v = fmaxf(v, dppf<0x141, 0xF>(v, v)); v = fmaxf(v, dppf<0x140, 0xF>(v, v)); return v;
; }
; template <int N, int M> DEVI void select16m(float (&k)[M][N], float (&res)[M], int i16) {
; #pragma unroll
;   for (int m = 0; m < M; ++m) res[m] = 0.f;
; #pragma unroll
;   for (int kk = 0; kk < 16; ++kk) {
;     float rm[M];
; #pragma unroll
;     for (int m = 0; m < M; ++m) rm[m] = row16_max(k[m][0]);
; #pragma unroll
;     for (int m = 0; m < M; ++m) {
;       const bool win = k[m][0] == rm[m];
; #pragma unroll
;       for (int j = 0; j < N - 1; ++j) k[m][j] = win ? k[m][j + 1] : k[m][j];
;       k[m][N - 1] = win ? -3.0e38f : k[m][N - 1];
;       res[m] = (i16 == kk) ? rm[m] : res[m];
;     }
;   }
; }
	v_cndmask_b32_e32 v17, v20, v23, vcc
	v_max_f32_dpp v30, v30, v30 quad_perm:[2,3,0,1] row_mask:0xf bank_mask:0xf
	v_cndmask_b32_e32 v18, v23, v24, vcc
	v_cndmask_b32_e32 v19, v24, v19, vcc
	v_max_f32_dpp v30, v30, v30 row_half_mirror row_mask:0xf bank_mask:0xf
	v_mov_b32_e32 v31, v30
	v_max_f32_e32 v24, v15, v15
	v_cndmask_b32_e64 v20, v25, v29, s[16:17]
	v_mov_b32_dpp v31, v31 row_mirror row_mask:0xf bank_mask:0xf
	v_max_f32_e32 v31, v31, v31
	v_max_f32_e32 v30, v30, v31
	v_cmp_eq_f32_e32 vcc, v26, v30
	v_max_f32_e32 v25, v7, v7
	v_cndmask_b32_e64 v5, v5, v30, s[16:17]
	v_cndmask_b32_e32 v23, v27, v4, vcc
	v_cndmask_b32_e32 v4, v4, v21, vcc
	v_cndmask_b32_e32 v3, v21, v3, vcc
	v_cndmask_b32_e32 v22, v26, v27, vcc
	v_max_f32_e32 v26, v16, v16
	v_max_f32_dpp v21, v15, v24 quad_perm:[1,0,3,2] row_mask:0xf bank_mask:0xf
	v_max_f32_e32 v27, v22, v22
	s_nop 0
	v_max_f32_dpp v21, v21, v21 quad_perm:[2,3,0,1] row_mask:0xf bank_mask:0xf
	s_nop 1
	v_max_f32_dpp v21, v21, v21 row_half_mirror row_mask:0xf bank_mask:0xf
	s_nop 1
	v_max_f32_dpp v21, v21, v21 row_mirror row_mask:0xf bank_mask:0xf
	v_cmp_eq_f32_e32 vcc, v15, v21
	v_cndmask_b32_e64 v6, v6, v21, s[82:83]
	v_max_f32_dpp v24, v7, v25 quad_perm:[1,0,3,2] row_mask:0xf bank_mask:0xf
	v_cndmask_b32_e32 v15, v15, v13, vcc
	v_cndmask_b32_e32 v13, v13, v10, vcc
	v_max_f32_dpp v24, v24, v24 quad_perm:[2,3,0,1] row_mask:0xf bank_mask:0xf
	v_cndmask_b32_e32 v8, v10, v8, vcc
	s_nop 0
	v_max_f32_dpp v24, v24, v24 row_half_mirror row_mask:0xf bank_mask:0xf
	s_nop 1
	v_max_f32_dpp v24, v24, v24 row_mirror row_mask:0xf bank_mask:0xf
	v_cmp_eq_f32_e32 vcc, v7, v24
	s_nop 0
	v_max_f32_dpp v25, v16, v26 quad_perm:[1,0,3,2] row_mask:0xf bank_mask:0xf
	v_cndmask_b32_e32 v7, v7, v9, vcc
	v_cndmask_b32_e32 v9, v9, v11, vcc
	v_max_f32_dpp v25, v25, v25 quad_perm:[2,3,0,1] row_mask:0xf bank_mask:0xf
	v_cndmask_b32_e32 v10, v11, v12, vcc
	v_cndmask_b32_e64 v11, v14, v24, s[82:83]
	v_max_f32_dpp v25, v25, v25 row_half_mirror row_mask:0xf bank_mask:0xf
	v_max_f32_e32 v21, v7, v7
	s_nop 0
	v_max_f32_dpp v25, v25, v25 row_mirror row_mask:0xf bank_mask:0xf
	v_cmp_eq_f32_e32 vcc, v16, v25
	s_nop 0
	v_max_f32_dpp v26, v22, v27 quad_perm:[1,0,3,2] row_mask:0xf bank_mask:0xf
	v_cndmask_b32_e32 v12, v16, v17, vcc
	v_cndmask_b32_e32 v14, v17, v18, vcc
	v_max_f32_dpp v26, v26, v26 quad_perm:[2,3,0,1] row_mask:0xf bank_mask:0xf
	v_cndmask_b32_e32 v16, v18, v19, vcc
	v_cndmask_b32_e64 v17, v20, v25, s[82:83]
	v_max_f32_dpp v26, v26, v26 row_half_mirror row_mask:0xf bank_mask:0xf
	v_mov_b32_e32 v27, v26
	v_max_f32_e32 v20, v15, v15
	s_nop 0
	v_mov_b32_dpp v27, v27 row_mirror row_mask:0xf bank_mask:0xf
	v_max_f32_e32 v27, v27, v27
	v_max_f32_e32 v26, v26, v27
	v_cmp_eq_f32_e32 vcc, v22, v26
	s_nop 1
	v_cndmask_b32_e32 v19, v23, v4, vcc
	v_cndmask_b32_e32 v3, v4, v3, vcc
	v_cndmask_b32_e64 v4, v5, v26, s[82:83]
	v_cndmask_b32_e32 v18, v22, v23, vcc
	v_max_f32_e32 v22, v12, v12
	v_max_f32_dpp v5, v15, v20 quad_perm:[1,0,3,2] row_mask:0xf bank_mask:0xf
	v_max_f32_e32 v23, v18, v18
	s_nop 0
	v_max_f32_dpp v5, v5, v5 quad_perm:[2,3,0,1] row_mask:0xf bank_mask:0xf
	s_nop 1
	v_max_f32_dpp v5, v5, v5 row_half_mirror row_mask:0xf bank_mask:0xf
	s_nop 1
	v_max_f32_dpp v5, v5, v5 row_mirror row_mask:0xf bank_mask:0xf
	v_cmp_eq_f32_e32 vcc, v15, v5
	v_cndmask_b32_e64 v5, v6, v5, s[84:85]
	v_max_f32_dpp v20, v7, v21 quad_perm:[1,0,3,2] row_mask:0xf bank_mask:0xf
	v_cndmask_b32_e32 v15, v15, v13, vcc
	v_cndmask_b32_e32 v8, v13, v8, vcc
	v_max_f32_dpp v20, v20, v20 quad_perm:[2,3,0,1] row_mask:0xf bank_mask:0xf
	s_nop 1
	v_max_f32_dpp v20, v20, v20 row_half_mirror row_mask:0xf bank_mask:0xf
	s_nop 1
	v_max_f32_dpp v20, v20, v20 row_mirror row_mask:0xf bank_mask:0xf
	v_cmp_eq_f32_e32 vcc, v7, v20
	s_nop 0
	v_max_f32_dpp v21, v12, v22 quad_perm:[1,0,3,2] row_mask:0xf bank_mask:0xf
	v_cndmask_b32_e32 v6, v7, v9, vcc
	v_cndmask_b32_e32 v7, v9, v10, vcc
	v_max_f32_dpp v21, v21, v21 quad_perm:[2,3,0,1] row_mask:0xf bank_mask:0xf
	v_cndmask_b32_e64 v9, v11, v20, s[84:85]
	s_nop 0
	v_max_f32_dpp v21, v21, v21 row_half_mirror row_mask:0xf bank_mask:0xf
	s_nop 1
	v_max_f32_dpp v21, v21, v21 row_mirror row_mask:0xf bank_mask:0xf
	v_cmp_eq_f32_e32 vcc, v12, v21
	s_nop 0
	s_nop 0
	v_cndmask_b32_e32 v10, v12, v14, vcc
	v_cndmask_b32_e32 v11, v14, v16, vcc
	v_max_f32_e32 v16, v15, v15
	v_max_f32_dpp v14, v15, v16 quad_perm:[1,0,3,2] row_mask:0xf bank_mask:0xf
	v_cndmask_b32_e64 v12, v17, v21, s[84:85]
	s_nop 0
	v_max_f32_dpp v14, v14, v14 quad_perm:[2,3,0,1] row_mask:0xf bank_mask:0xf
	v_max_f32_e32 v17, v6, v6
	v_max_f32_dpp v22, v18, v23 quad_perm:[1,0,3,2] row_mask:0xf bank_mask:0xf
	v_max_f32_dpp v14, v14, v14 row_half_mirror row_mask:0xf bank_mask:0xf
	s_nop 0
	s_nop 0
	v_max_f32_dpp v14, v14, v14 row_mirror row_mask:0xf bank_mask:0xf
	v_max_f32_dpp v16, v6, v17 quad_perm:[1,0,3,2] row_mask:0xf bank_mask:0xf
	v_max_f32_dpp v22, v22, v22 quad_perm:[2,3,0,1] row_mask:0xf bank_mask:0xf
	s_nop 0
	v_max_f32_dpp v16, v16, v16 quad_perm:[2,3,0,1] row_mask:0xf bank_mask:0xf
	v_max_f32_dpp v22, v22, v22 row_half_mirror row_mask:0xf bank_mask:0xf
	s_nop 0
	v_max_f32_dpp v16, v16, v16 row_half_mirror row_mask:0xf bank_mask:0xf
	v_mov_b32_e32 v23, v22
	v_cndmask_b32_e64 v5, v5, v14, s[86:87]
	s_nop 0
	v_mov_b32_dpp v23, v23 row_mirror row_mask:0xf bank_mask:0xf
	v_max_f32_e32 v23, v23, v23
	v_max_f32_e32 v22, v22, v23
	v_max_f32_dpp v16, v16, v16 row_mirror row_mask:0xf bank_mask:0xf
	v_cmp_eq_f32_e32 vcc, v18, v22
	v_cndmask_b32_e64 v4, v4, v22, s[84:85]
	s_nop 0
	v_cndmask_b32_e32 v13, v18, v19, vcc
	v_max_f32_e32 v18, v10, v10
; DEVI float shfll(float v, int src) { return __int_as_float(__builtin_amdgcn_ds_bpermute(src << 2, __float_as_int(v))); }
; DEVI float pack_key(float v, int idx) { return __uint_as_float((__float_as_uint(v) & ~127u) | (unsigned)(127 - idx)); }
; #define CE(a, b) do { float hi_ = fmaxf(a, b), lo_ = fminf(a, b); a = hi_; b = lo_; } while (0)
; template <int N, int M> DEVI void select16m(float (&k)[M][N], float (&res)[M], int i16) {
; #pragma unroll
;   for (int m = 0; m < M; ++m) res[m] = 0.f;
; #pragma unroll
;   for (int kk = 0; kk < 16; ++kk) {
;     float rm[M];
; #pragma unroll
;     for (int m = 0; m < M; ++m) rm[m] = row16_max(k[m][0]);
; #pragma unroll
;     for (int m = 0; m < M; ++m) {
;       const bool win = k[m][0] == rm[m];
; #pragma unroll
;       for (int j = 0; j < N - 1; ++j) k[m][j] = win ? k[m][j + 1] : k[m][j];
;       k[m][N - 1] = win ? -3.0e38f : k[m][N - 1];
;       res[m] = (i16 == kk) ? rm[m] : res[m];
;     }
;   }
; }
; DEVI void peer_topk_phase(const Params& p, int layer, char* lds) {
;     ...
;       float c[2][4], best[2];
; #pragma unroll
;       for (int ps = 0; ps < 2; ++ps) {
; #pragma unroll
;         for (int m = 0; m < 4; ++m) {
;           const float v1 = shfll(key[ps * 2], row4 * 16 + (sa[m] & 15)), v2 = shfll(key[ps * 2 + 1], row4 * 16 + (sb[m] & 15));
;           c[ps][m] = (sa[m] < 16) ? pack_key(v1 + v2, i16 + 16 * m) : -3.0e38f;
;         }
;         CE(c[ps][0], c[ps][1]); CE(c[ps][2], c[ps][3]); CE(c[ps][0], c[ps][2]); CE(c[ps][1], c[ps][3]); CE(c[ps][1], c[ps][2]);
;       }
	v_max_f32_dpp v17, v10, v18 quad_perm:[1,0,3,2] row_mask:0xf bank_mask:0xf
	v_cndmask_b32_e32 v3, v19, v3, vcc
	v_max_f32_e32 v19, v13, v13
	v_max_f32_dpp v17, v17, v17 quad_perm:[2,3,0,1] row_mask:0xf bank_mask:0xf
	v_cmp_eq_f32_e32 vcc, v15, v14
	s_nop 0
	v_max_f32_dpp v17, v17, v17 row_half_mirror row_mask:0xf bank_mask:0xf
	v_cndmask_b32_e32 v8, v15, v8, vcc
	v_cmp_eq_f32_e32 vcc, v6, v16
	v_max_f32_dpp v17, v17, v17 row_mirror row_mask:0xf bank_mask:0xf
	s_nop 0
	v_cndmask_b32_e32 v6, v6, v7, vcc
	v_cmp_eq_f32_e32 vcc, v10, v17
	v_max_f32_dpp v18, v13, v19 quad_perm:[1,0,3,2] row_mask:0xf bank_mask:0xf
	v_cndmask_b32_e64 v7, v9, v16, s[86:87]
	v_cndmask_b32_e32 v9, v10, v11, vcc
	v_max_f32_dpp v18, v18, v18 quad_perm:[2,3,0,1] row_mask:0xf bank_mask:0xf
	v_cndmask_b32_e64 v10, v12, v17, s[86:87]
	s_nop 0
	v_max_f32_dpp v18, v18, v18 row_half_mirror row_mask:0xf bank_mask:0xf
	s_nop 1
	v_max_f32_dpp v18, v18, v18 row_mirror row_mask:0xf bank_mask:0xf
	v_cndmask_b32_e64 v11, v4, v18, s[86:87]
	v_max_f32_e32 v4, v8, v8
	v_mov_b32_dpp v8, v8 quad_perm:[1,0,3,2] row_mask:0xf bank_mask:0xf
	v_max_f32_e32 v8, v8, v8
	v_max_f32_e32 v4, v4, v8
	v_cmp_eq_f32_e32 vcc, v13, v18
	s_nop 0
	v_max_f32_dpp v4, v4, v4 quad_perm:[2,3,0,1] row_mask:0xf bank_mask:0xf
	v_cndmask_b32_e32 v3, v13, v3, vcc
	s_nop 0
	v_max_f32_dpp v4, v4, v4 row_half_mirror row_mask:0xf bank_mask:0xf
	s_nop 1
	v_max_f32_dpp v4, v4, v4 row_mirror row_mask:0xf bank_mask:0xf
	v_max_f32_e32 v8, v6, v6
	v_mov_b32_dpp v6, v6 quad_perm:[1,0,3,2] row_mask:0xf bank_mask:0xf
	v_max_f32_e32 v6, v6, v6
	v_max_f32_e32 v6, v8, v6
	s_nop 1
	v_max_f32_dpp v6, v6, v6 quad_perm:[2,3,0,1] row_mask:0xf bank_mask:0xf
	s_nop 1
	v_max_f32_dpp v6, v6, v6 row_half_mirror row_mask:0xf bank_mask:0xf
	s_nop 1
	v_max_f32_dpp v6, v6, v6 row_mirror row_mask:0xf bank_mask:0xf
	v_max_f32_e32 v8, v9, v9
	v_mov_b32_dpp v9, v9 quad_perm:[1,0,3,2] row_mask:0xf bank_mask:0xf
	v_max_f32_e32 v9, v9, v9
	v_max_f32_e32 v8, v8, v9
	v_cndmask_b32_e64 v6, v7, v6, s[88:89]
	ds_bpermute_b32 v12, v151, v6
	v_max_f32_dpp v8, v8, v8 quad_perm:[2,3,0,1] row_mask:0xf bank_mask:0xf
	s_nop 1
	v_max_f32_dpp v8, v8, v8 row_half_mirror row_mask:0xf bank_mask:0xf
	s_nop 1
	v_max_f32_dpp v8, v8, v8 row_mirror row_mask:0xf bank_mask:0xf
	v_max_f32_e32 v9, v3, v3
	v_mov_b32_dpp v3, v3 quad_perm:[1,0,3,2] row_mask:0xf bank_mask:0xf
	v_max_f32_e32 v3, v3, v3
	v_max_f32_e32 v3, v9, v3
	s_nop 1
	v_max_f32_dpp v3, v3, v3 quad_perm:[2,3,0,1] row_mask:0xf bank_mask:0xf
	s_nop 1
	v_max_f32_dpp v3, v3, v3 row_half_mirror row_mask:0xf bank_mask:0xf
	s_nop 1
	v_max_f32_dpp v9, v3, v3 row_mirror row_mask:0xf bank_mask:0xf
	v_cndmask_b32_e64 v3, v5, v4, s[88:89]
	ds_bpermute_b32 v7, v150, v3
	v_cndmask_b32_e64 v4, v10, v8, s[88:89]
	ds_bpermute_b32 v8, v152, v3
	ds_bpermute_b32 v10, v153, v6
	v_cndmask_b32_e64 v5, v11, v9, s[88:89]
	s_waitcnt lgkmcnt(2)
	v_add_f32_e32 v7, v7, v12
	ds_bpermute_b32 v9, v154, v3
	ds_bpermute_b32 v11, v156, v3
	s_waitcnt lgkmcnt(2)
	v_add_f32_e32 v8, v8, v10
	ds_bpermute_b32 v10, v155, v6
	ds_bpermute_b32 v12, v157, v6
	v_and_or_b32 v7, v7, s23, v138
	v_and_or_b32 v8, v8, s23, v143
	v_cndmask_b32_e64 v7, v226, v7, s[90:91]
	s_waitcnt lgkmcnt(1)
	v_add_f32_e32 v9, v9, v10
	s_waitcnt lgkmcnt(0)
	v_add_f32_e32 v10, v11, v12
	v_cndmask_b32_e64 v8, v226, v8, s[92:93]
	v_and_or_b32 v9, v9, s23, v144
	v_and_or_b32 v10, v10, s23, v145
	v_cndmask_b32_e64 v9, v226, v9, s[94:95]
	v_cndmask_b32_e64 v10, v226, v10, s[76:77]
	v_max_f32_e32 v8, v8, v8
	v_max_f32_e32 v7, v7, v7
	v_max_f32_e32 v11, v7, v8
	v_min_f32_e32 v7, v7, v8
	v_max_f32_e32 v8, v10, v10
	v_max_f32_e32 v9, v9, v9
	v_max_f32_e32 v10, v9, v8
	v_min_f32_e32 v8, v9, v8
	v_max_f32_e32 v9, v11, v10
	v_min_f32_e32 v10, v11, v10
	v_max_f32_e32 v11, v7, v8
	v_min_f32_e32 v7, v7, v8
	ds_bpermute_b32 v8, v150, v4
	ds_bpermute_b32 v12, v151, v5
	ds_bpermute_b32 v14, v152, v4
	ds_bpermute_b32 v15, v153, v5
	v_max_f32_e32 v13, v11, v10
	v_min_f32_e32 v10, v11, v10
	s_waitcnt lgkmcnt(2)
	v_add_f32_e32 v8, v8, v12
	ds_bpermute_b32 v12, v154, v4
	s_waitcnt lgkmcnt(1)
	v_add_f32_e32 v11, v14, v15
	ds_bpermute_b32 v14, v155, v5
	ds_bpermute_b32 v15, v156, v4
	ds_bpermute_b32 v16, v157, v5
	v_and_or_b32 v8, v8, s23, v138
	v_and_or_b32 v11, v11, s23, v143
	s_waitcnt lgkmcnt(2)
	v_add_f32_e32 v12, v12, v14
	v_cndmask_b32_e64 v8, v226, v8, s[90:91]
	s_waitcnt lgkmcnt(0)
; DEVI float row16_max(float v) {
;   v = fmaxf(v, dppf<0xB1, 0xF>(v, v)); v = fmaxf(v, dppf<0x4E, 0xF>(v, v)); v = fmaxf(v, dppf<0x141, 0xF>(v, v)); v = fmaxf(v, dppf<0x140, 0xF>(v, v)); return v;
; }
; template <int N, int M> DEVI void select16m(float (&k)[M][N], float (&res)[M], int i16) {
; #pragma unroll
;   for (int m = 0; m < M; ++m) res[m] = 0.f;
; #pragma unroll
;   for (int kk = 0; kk < 16; ++kk) {
;     float rm[M];
; #pragma unroll
;     for (int m = 0; m < M; ++m) rm[m] = row16_max(k[m][0]);
; #pragma unroll
;     for (int m = 0; m < M; ++m) {
;       const bool win = k[m][0] == rm[m];
; #pragma unroll
;       for (int j = 0; j < N - 1; ++j) k[m][j] = win ? k[m][j + 1] : k[m][j];
;       k[m][N - 1] = win ? -3.0e38f : k[m][N - 1];
;       res[m] = (i16 == kk) ? rm[m] : res[m];
;     }
;   }
; }
	v_add_f32_e32 v14, v15, v16
	v_cndmask_b32_e64 v11, v226, v11, s[92:93]
	v_and_or_b32 v12, v12, s23, v144
	v_and_or_b32 v14, v14, s23, v145
	v_cndmask_b32_e64 v12, v226, v12, s[94:95]
	v_cndmask_b32_e64 v14, v226, v14, s[76:77]
	v_max_f32_e32 v11, v11, v11
	v_max_f32_e32 v8, v8, v8
	v_max_f32_e32 v15, v8, v11
	v_min_f32_e32 v8, v8, v11
	v_max_f32_e32 v11, v14, v14
	v_max_f32_e32 v12, v12, v12
	v_max_f32_e32 v14, v12, v11
	v_min_f32_e32 v11, v12, v11
	v_max_f32_e32 v12, v15, v14
	v_min_f32_e32 v14, v15, v14
	v_max_f32_e32 v15, v8, v11
	v_min_f32_e32 v8, v8, v11
	v_max_f32_e32 v11, v15, v14
	v_min_f32_e32 v14, v15, v14
	s_nop 1
	v_max_f32_dpp v15, v9, v9 quad_perm:[1,0,3,2] row_mask:0xf bank_mask:0xf
	s_nop 1
	v_max_f32_dpp v15, v15, v15 quad_perm:[2,3,0,1] row_mask:0xf bank_mask:0xf
	s_nop 1
	v_max_f32_dpp v15, v15, v15 row_half_mirror row_mask:0xf bank_mask:0xf
	s_nop 1
	v_max_f32_dpp v15, v15, v15 row_mirror row_mask:0xf bank_mask:0xf
	v_cmp_eq_f32_e32 vcc, v9, v15
	v_cndmask_b32_e64 v15, 0, v15, s[38:39]
	v_max_f32_dpp v16, v12, v12 quad_perm:[1,0,3,2] row_mask:0xf bank_mask:0xf
	v_cndmask_b32_e32 v9, v9, v13, vcc
	v_cndmask_b32_e32 v13, v13, v10, vcc
	v_max_f32_dpp v16, v16, v16 quad_perm:[2,3,0,1] row_mask:0xf bank_mask:0xf
	v_cndmask_b32_e32 v10, v10, v7, vcc
	v_cndmask_b32_e32 v7, v7, v226, vcc
	v_max_f32_dpp v16, v16, v16 row_half_mirror row_mask:0xf bank_mask:0xf
	s_nop 1
	v_max_f32_dpp v16, v16, v16 row_mirror row_mask:0xf bank_mask:0xf
	v_cmp_eq_f32_e32 vcc, v12, v16
	v_cndmask_b32_e64 v16, 0, v16, s[38:39]
	v_max_f32_dpp v17, v9, v9 quad_perm:[1,0,3,2] row_mask:0xf bank_mask:0xf
	v_cndmask_b32_e32 v12, v12, v11, vcc
	v_cndmask_b32_e32 v11, v11, v14, vcc
	v_max_f32_dpp v17, v17, v17 quad_perm:[2,3,0,1] row_mask:0xf bank_mask:0xf
	v_cndmask_b32_e32 v14, v14, v8, vcc
	v_cndmask_b32_e32 v8, v8, v226, vcc
	v_max_f32_dpp v17, v17, v17 row_half_mirror row_mask:0xf bank_mask:0xf
	s_nop 1
	v_max_f32_dpp v17, v17, v17 row_mirror row_mask:0xf bank_mask:0xf
	v_cmp_eq_f32_e32 vcc, v9, v17
	v_cndmask_b32_e64 v15, v15, v17, s[40:41]
	v_max_f32_dpp v18, v12, v12 quad_perm:[1,0,3,2] row_mask:0xf bank_mask:0xf
	v_cndmask_b32_e32 v9, v9, v13, vcc
	s_nop 0
	v_max_f32_dpp v18, v18, v18 quad_perm:[2,3,0,1] row_mask:0xf bank_mask:0xf
	s_nop 1
	v_max_f32_dpp v18, v18, v18 row_half_mirror row_mask:0xf bank_mask:0xf
	v_max_f32_dpp v17, v9, v9 quad_perm:[1,0,3,2] row_mask:0xf bank_mask:0xf
	v_cndmask_b32_e32 v13, v13, v10, vcc
	v_max_f32_dpp v18, v18, v18 row_mirror row_mask:0xf bank_mask:0xf
	v_cndmask_b32_e32 v10, v10, v7, vcc
	v_cndmask_b32_e32 v7, v7, v226, vcc
	v_cmp_eq_f32_e32 vcc, v12, v18
	v_cndmask_b32_e64 v16, v16, v18, s[40:41]
	s_nop 0
	v_cndmask_b32_e32 v12, v12, v11, vcc
	v_cndmask_b32_e32 v11, v11, v14, vcc
	v_max_f32_dpp v17, v17, v17 quad_perm:[2,3,0,1] row_mask:0xf bank_mask:0xf
	v_cndmask_b32_e32 v14, v14, v8, vcc
	v_cndmask_b32_e32 v8, v8, v226, vcc
	v_max_f32_dpp v17, v17, v17 row_half_mirror row_mask:0xf bank_mask:0xf
	s_nop 1
	v_max_f32_dpp v17, v17, v17 row_mirror row_mask:0xf bank_mask:0xf
	v_cmp_eq_f32_e32 vcc, v9, v17
	v_cndmask_b32_e64 v15, v15, v17, s[42:43]
	v_max_f32_dpp v18, v12, v12 quad_perm:[1,0,3,2] row_mask:0xf bank_mask:0xf
	v_cndmask_b32_e32 v9, v9, v13, vcc
	s_nop 0
	v_max_f32_dpp v18, v18, v18 quad_perm:[2,3,0,1] row_mask:0xf bank_mask:0xf
	s_nop 1
	v_max_f32_dpp v18, v18, v18 row_half_mirror row_mask:0xf bank_mask:0xf
	v_max_f32_dpp v17, v9, v9 quad_perm:[1,0,3,2] row_mask:0xf bank_mask:0xf
	v_cndmask_b32_e32 v13, v13, v10, vcc
	v_max_f32_dpp v18, v18, v18 row_mirror row_mask:0xf bank_mask:0xf
	v_cndmask_b32_e32 v10, v10, v7, vcc
	v_cndmask_b32_e32 v7, v7, v226, vcc
	v_cmp_eq_f32_e32 vcc, v12, v18
	v_cndmask_b32_e64 v16, v16, v18, s[42:43]
	s_nop 0
	v_cndmask_b32_e32 v12, v12, v11, vcc
	v_cndmask_b32_e32 v11, v11, v14, vcc
	v_max_f32_dpp v17, v17, v17 quad_perm:[2,3,0,1] row_mask:0xf bank_mask:0xf
	v_cndmask_b32_e32 v14, v14, v8, vcc
	v_cndmask_b32_e32 v8, v8, v226, vcc
	v_max_f32_dpp v17, v17, v17 row_half_mirror row_mask:0xf bank_mask:0xf
	s_nop 1
	v_max_f32_dpp v17, v17, v17 row_mirror row_mask:0xf bank_mask:0xf
	v_cmp_eq_f32_e32 vcc, v9, v17
	v_cndmask_b32_e64 v15, v15, v17, s[44:45]
	v_max_f32_dpp v18, v12, v12 quad_perm:[1,0,3,2] row_mask:0xf bank_mask:0xf
	v_cndmask_b32_e32 v9, v9, v13, vcc
	s_nop 0
	v_max_f32_dpp v18, v18, v18 quad_perm:[2,3,0,1] row_mask:0xf bank_mask:0xf
	s_nop 1
	v_max_f32_dpp v18, v18, v18 row_half_mirror row_mask:0xf bank_mask:0xf
	v_max_f32_dpp v17, v9, v9 quad_perm:[1,0,3,2] row_mask:0xf bank_mask:0xf
	v_cndmask_b32_e32 v13, v13, v10, vcc
	v_max_f32_dpp v18, v18, v18 row_mirror row_mask:0xf bank_mask:0xf
	v_cndmask_b32_e32 v10, v10, v7, vcc
	v_cndmask_b32_e32 v7, v7, v226, vcc
	v_cmp_eq_f32_e32 vcc, v12, v18
	v_cndmask_b32_e64 v16, v16, v18, s[44:45]
	s_nop 0
	v_cndmask_b32_e32 v12, v12, v11, vcc
	v_cndmask_b32_e32 v11, v11, v14, vcc
	v_max_f32_dpp v17, v17, v17 quad_perm:[2,3,0,1] row_mask:0xf bank_mask:0xf
	v_cndmask_b32_e32 v14, v14, v8, vcc
	v_cndmask_b32_e32 v8, v8, v226, vcc
	v_max_f32_dpp v17, v17, v17 row_half_mirror row_mask:0xf bank_mask:0xf
	s_nop 1
	v_max_f32_dpp v17, v17, v17 row_mirror row_mask:0xf bank_mask:0xf
	v_cmp_eq_f32_e32 vcc, v9, v17
	v_cndmask_b32_e64 v15, v15, v17, s[46:47]
	v_max_f32_dpp v18, v12, v12 quad_perm:[1,0,3,2] row_mask:0xf bank_mask:0xf
	v_cndmask_b32_e32 v9, v9, v13, vcc
	s_nop 0
	v_max_f32_dpp v18, v18, v18 quad_perm:[2,3,0,1] row_mask:0xf bank_mask:0xf
	v_cndmask_b32_e32 v13, v13, v10, vcc
	s_nop 0
	v_max_f32_dpp v18, v18, v18 row_half_mirror row_mask:0xf bank_mask:0xf
	v_cndmask_b32_e32 v10, v10, v7, vcc
	v_cndmask_b32_e32 v7, v7, v226, vcc
; DEVI float row16_max(float v) {
;   v = fmaxf(v, dppf<0xB1, 0xF>(v, v)); v = fmaxf(v, dppf<0x4E, 0xF>(v, v)); v = fmaxf(v, dppf<0x141, 0xF>(v, v)); v = fmaxf(v, dppf<0x140, 0xF>(v, v)); return v;
; }
; template <int N, int M> DEVI void select16m(float (&k)[M][N], float (&res)[M], int i16) {
; #pragma unroll
;   for (int m = 0; m < M; ++m) res[m] = 0.f;
; #pragma unroll
;   for (int kk = 0; kk < 16; ++kk) {
;     float rm[M];
; #pragma unroll
;     for (int m = 0; m < M; ++m) rm[m] = row16_max(k[m][0]);
; #pragma unroll
;     for (int m = 0; m < M; ++m) {
;       const bool win = k[m][0] == rm[m];
; #pragma unroll
;       for (int j = 0; j < N - 1; ++j) k[m][j] = win ? k[m][j + 1] : k[m][j];
;       k[m][N - 1] = win ? -3.0e38f : k[m][N - 1];
;       res[m] = (i16 == kk) ? rm[m] : res[m];
;     }
;   }
; }
	v_max_f32_dpp v18, v18, v18 row_mirror row_mask:0xf bank_mask:0xf
	v_cmp_eq_f32_e32 vcc, v12, v18
	v_cndmask_b32_e64 v16, v16, v18, s[46:47]
	v_max_f32_e32 v18, v9, v9
	v_max_f32_dpp v17, v9, v18 quad_perm:[1,0,3,2] row_mask:0xf bank_mask:0xf
	v_cndmask_b32_e32 v12, v12, v11, vcc
	v_max_f32_e32 v19, v12, v12
	v_max_f32_dpp v17, v17, v17 quad_perm:[2,3,0,1] row_mask:0xf bank_mask:0xf
	v_cndmask_b32_e32 v11, v11, v14, vcc
	v_cndmask_b32_e32 v14, v14, v8, vcc
	v_max_f32_dpp v17, v17, v17 row_half_mirror row_mask:0xf bank_mask:0xf
	v_cndmask_b32_e32 v8, v8, v226, vcc
	s_nop 0
	v_max_f32_dpp v17, v17, v17 row_mirror row_mask:0xf bank_mask:0xf
	v_cmp_eq_f32_e32 vcc, v9, v17
	v_cndmask_b32_e64 v15, v15, v17, s[48:49]
	v_max_f32_dpp v18, v12, v19 quad_perm:[1,0,3,2] row_mask:0xf bank_mask:0xf
	v_cndmask_b32_e32 v9, v9, v13, vcc
	s_nop 0
	v_max_f32_dpp v18, v18, v18 quad_perm:[2,3,0,1] row_mask:0xf bank_mask:0xf
	v_cndmask_b32_e32 v13, v13, v10, vcc
	s_nop 0
	v_max_f32_dpp v18, v18, v18 row_half_mirror row_mask:0xf bank_mask:0xf
	v_cndmask_b32_e32 v10, v10, v7, vcc
	v_cndmask_b32_e32 v7, v7, v226, vcc
	v_max_f32_dpp v18, v18, v18 row_mirror row_mask:0xf bank_mask:0xf
	v_cmp_eq_f32_e32 vcc, v12, v18
	v_cndmask_b32_e64 v16, v16, v18, s[48:49]
	v_max_f32_e32 v18, v9, v9
	v_max_f32_dpp v17, v9, v18 quad_perm:[1,0,3,2] row_mask:0xf bank_mask:0xf
	v_cndmask_b32_e32 v12, v12, v11, vcc
	v_max_f32_e32 v19, v12, v12
	v_max_f32_dpp v17, v17, v17 quad_perm:[2,3,0,1] row_mask:0xf bank_mask:0xf
	v_cndmask_b32_e32 v11, v11, v14, vcc
	v_cndmask_b32_e32 v14, v14, v8, vcc
	v_max_f32_dpp v17, v17, v17 row_half_mirror row_mask:0xf bank_mask:0xf
	v_cndmask_b32_e32 v8, v8, v226, vcc
	s_nop 0
	v_max_f32_dpp v17, v17, v17 row_mirror row_mask:0xf bank_mask:0xf
	v_cmp_eq_f32_e32 vcc, v9, v17
	v_cndmask_b32_e64 v15, v15, v17, s[50:51]
	v_max_f32_dpp v18, v12, v19 quad_perm:[1,0,3,2] row_mask:0xf bank_mask:0xf
	v_cndmask_b32_e32 v9, v9, v13, vcc
	s_nop 0
	v_max_f32_dpp v18, v18, v18 quad_perm:[2,3,0,1] row_mask:0xf bank_mask:0xf
	v_cndmask_b32_e32 v13, v13, v10, vcc
	s_nop 0
	v_max_f32_dpp v18, v18, v18 row_half_mirror row_mask:0xf bank_mask:0xf
	v_cndmask_b32_e32 v10, v10, v7, vcc
	v_cndmask_b32_e32 v7, v7, v226, vcc
	v_max_f32_dpp v18, v18, v18 row_mirror row_mask:0xf bank_mask:0xf
	v_cmp_eq_f32_e32 vcc, v12, v18
	v_cndmask_b32_e64 v16, v16, v18, s[50:51]
	v_max_f32_e32 v18, v9, v9
	v_max_f32_dpp v17, v9, v18 quad_perm:[1,0,3,2] row_mask:0xf bank_mask:0xf
	v_cndmask_b32_e32 v12, v12, v11, vcc
	v_max_f32_e32 v19, v12, v12
	v_max_f32_dpp v17, v17, v17 quad_perm:[2,3,0,1] row_mask:0xf bank_mask:0xf
	v_cndmask_b32_e32 v11, v11, v14, vcc
	v_cndmask_b32_e32 v14, v14, v8, vcc
	v_max_f32_dpp v17, v17, v17 row_half_mirror row_mask:0xf bank_mask:0xf
	v_cndmask_b32_e32 v8, v8, v226, vcc
	s_nop 0
	v_max_f32_dpp v17, v17, v17 row_mirror row_mask:0xf bank_mask:0xf
	v_cmp_eq_f32_e32 vcc, v9, v17
	v_cndmask_b32_e64 v15, v15, v17, s[52:53]
	v_max_f32_dpp v18, v12, v19 quad_perm:[1,0,3,2] row_mask:0xf bank_mask:0xf
	v_cndmask_b32_e32 v9, v9, v13, vcc
	s_nop 0
	v_max_f32_dpp v18, v18, v18 quad_perm:[2,3,0,1] row_mask:0xf bank_mask:0xf
	v_cndmask_b32_e32 v13, v13, v10, vcc
	s_nop 0
	v_max_f32_dpp v18, v18, v18 row_half_mirror row_mask:0xf bank_mask:0xf
	v_cndmask_b32_e32 v10, v10, v7, vcc
	v_cndmask_b32_e32 v7, v7, v226, vcc
	v_max_f32_dpp v18, v18, v18 row_mirror row_mask:0xf bank_mask:0xf
	v_cmp_eq_f32_e32 vcc, v12, v18
	v_cndmask_b32_e64 v16, v16, v18, s[52:53]
	v_max_f32_e32 v18, v9, v9
	v_max_f32_dpp v17, v9, v18 quad_perm:[1,0,3,2] row_mask:0xf bank_mask:0xf
	v_cndmask_b32_e32 v12, v12, v11, vcc
	v_max_f32_e32 v19, v12, v12
	v_max_f32_dpp v17, v17, v17 quad_perm:[2,3,0,1] row_mask:0xf bank_mask:0xf
	v_cndmask_b32_e32 v11, v11, v14, vcc
	v_cndmask_b32_e32 v14, v14, v8, vcc
	v_max_f32_dpp v17, v17, v17 row_half_mirror row_mask:0xf bank_mask:0xf
	v_cndmask_b32_e32 v8, v8, v226, vcc
	s_nop 0
	v_max_f32_dpp v17, v17, v17 row_mirror row_mask:0xf bank_mask:0xf
	v_cmp_eq_f32_e32 vcc, v9, v17
	v_cndmask_b32_e64 v15, v15, v17, s[54:55]
	v_max_f32_dpp v18, v12, v19 quad_perm:[1,0,3,2] row_mask:0xf bank_mask:0xf
	v_cndmask_b32_e32 v9, v9, v13, vcc
	s_nop 0
	v_max_f32_dpp v18, v18, v18 quad_perm:[2,3,0,1] row_mask:0xf bank_mask:0xf
	v_cndmask_b32_e32 v13, v13, v10, vcc
	s_nop 0
	v_max_f32_dpp v18, v18, v18 row_half_mirror row_mask:0xf bank_mask:0xf
	v_cndmask_b32_e32 v10, v10, v7, vcc
	v_cndmask_b32_e32 v7, v7, v226, vcc
	v_max_f32_dpp v18, v18, v18 row_mirror row_mask:0xf bank_mask:0xf
	v_cmp_eq_f32_e32 vcc, v12, v18
	v_cndmask_b32_e64 v16, v16, v18, s[54:55]
	v_max_f32_e32 v18, v9, v9
	v_max_f32_dpp v17, v9, v18 quad_perm:[1,0,3,2] row_mask:0xf bank_mask:0xf
	v_cndmask_b32_e32 v12, v12, v11, vcc
	v_max_f32_e32 v19, v12, v12
	v_max_f32_dpp v17, v17, v17 quad_perm:[2,3,0,1] row_mask:0xf bank_mask:0xf
	v_cndmask_b32_e32 v11, v11, v14, vcc
	v_cndmask_b32_e32 v14, v14, v8, vcc
	v_max_f32_dpp v17, v17, v17 row_half_mirror row_mask:0xf bank_mask:0xf
	v_cndmask_b32_e32 v8, v8, v226, vcc
	s_nop 0
	v_max_f32_dpp v17, v17, v17 row_mirror row_mask:0xf bank_mask:0xf
	v_cmp_eq_f32_e32 vcc, v9, v17
	v_cndmask_b32_e64 v15, v15, v17, s[56:57]
	v_max_f32_dpp v18, v12, v19 quad_perm:[1,0,3,2] row_mask:0xf bank_mask:0xf
	v_cndmask_b32_e32 v9, v9, v13, vcc
	s_nop 0
	v_max_f32_dpp v18, v18, v18 quad_perm:[2,3,0,1] row_mask:0xf bank_mask:0xf
	v_cndmask_b32_e32 v13, v13, v10, vcc
	s_nop 0
	v_max_f32_dpp v18, v18, v18 row_half_mirror row_mask:0xf bank_mask:0xf
	v_cndmask_b32_e32 v10, v10, v7, vcc
	v_cndmask_b32_e32 v7, v7, v226, vcc
	v_max_f32_dpp v18, v18, v18 row_mirror row_mask:0xf bank_mask:0xf
	v_cmp_eq_f32_e32 vcc, v12, v18
; DEVI float shfll(float v, int src) { return __int_as_float(__builtin_amdgcn_ds_bpermute(src << 2, __float_as_int(v))); }
; DEVI int key_idx(float k) { return 127 - (int)(__float_as_uint(k) & 127u); }
; template <int N, int M> DEVI void select16m(float (&k)[M][N], float (&res)[M], int i16) {
; #pragma unroll
;   for (int m = 0; m < M; ++m) res[m] = 0.f;
; #pragma unroll
;   for (int kk = 0; kk < 16; ++kk) {
;     float rm[M];
; #pragma unroll
;     for (int m = 0; m < M; ++m) rm[m] = row16_max(k[m][0]);
; #pragma unroll
;     for (int m = 0; m < M; ++m) {
;       const bool win = k[m][0] == rm[m];
; #pragma unroll
;       for (int j = 0; j < N - 1; ++j) k[m][j] = win ? k[m][j + 1] : k[m][j];
;       k[m][N - 1] = win ? -3.0e38f : k[m][N - 1];
;       res[m] = (i16 == kk) ? rm[m] : res[m];
;     }
;   }
; }
; DEVI void peer_topk_phase(const Params& p, int layer, char* lds) {
;     ...
;       for (int ps = 0; ps < 2; ++ps) {
;         const int tok = w * 8 + ps * 4 + row4;
;         const int cs = key_idx(best[ps]), st_ = stair[cs & 63];
;         const int e1 = key_idx(shfll(key[ps * 2], row4 * 16 + (st_ & 15))), e2 = key_idx(shfll(key[ps * 2 + 1], row4 * 16 + ((st_ >> 8) & 15)));
;         const float mx = row16_max(best[ps]);
	v_cndmask_b32_e64 v16, v16, v18, s[56:57]
	v_max_f32_e32 v18, v9, v9
	v_max_f32_dpp v17, v9, v18 quad_perm:[1,0,3,2] row_mask:0xf bank_mask:0xf
	v_cndmask_b32_e32 v12, v12, v11, vcc
	v_max_f32_e32 v19, v12, v12
	v_max_f32_dpp v17, v17, v17 quad_perm:[2,3,0,1] row_mask:0xf bank_mask:0xf
	v_cndmask_b32_e32 v11, v11, v14, vcc
	v_cndmask_b32_e32 v14, v14, v8, vcc
	v_max_f32_dpp v17, v17, v17 row_half_mirror row_mask:0xf bank_mask:0xf
	v_cndmask_b32_e32 v8, v8, v226, vcc
	s_nop 0
	v_max_f32_dpp v17, v17, v17 row_mirror row_mask:0xf bank_mask:0xf
	v_cmp_eq_f32_e32 vcc, v9, v17
	v_cndmask_b32_e64 v15, v15, v17, s[58:59]
	v_max_f32_dpp v18, v12, v19 quad_perm:[1,0,3,2] row_mask:0xf bank_mask:0xf
	v_cndmask_b32_e32 v9, v9, v13, vcc
	s_nop 0
	v_max_f32_dpp v18, v18, v18 quad_perm:[2,3,0,1] row_mask:0xf bank_mask:0xf
	v_cndmask_b32_e32 v13, v13, v10, vcc
	s_nop 0
	v_max_f32_dpp v18, v18, v18 row_half_mirror row_mask:0xf bank_mask:0xf
	v_cndmask_b32_e32 v10, v10, v7, vcc
	v_cndmask_b32_e32 v7, v7, v226, vcc
	v_max_f32_dpp v18, v18, v18 row_mirror row_mask:0xf bank_mask:0xf
	v_cmp_eq_f32_e32 vcc, v12, v18
	v_cndmask_b32_e64 v16, v16, v18, s[58:59]
	v_max_f32_e32 v18, v9, v9
	v_max_f32_dpp v17, v9, v18 quad_perm:[1,0,3,2] row_mask:0xf bank_mask:0xf
	v_cndmask_b32_e32 v12, v12, v11, vcc
	v_max_f32_e32 v19, v12, v12
	v_max_f32_dpp v17, v17, v17 quad_perm:[2,3,0,1] row_mask:0xf bank_mask:0xf
	v_cndmask_b32_e32 v11, v11, v14, vcc
	v_cndmask_b32_e32 v14, v14, v8, vcc
	v_max_f32_dpp v17, v17, v17 row_half_mirror row_mask:0xf bank_mask:0xf
	v_cndmask_b32_e32 v8, v8, v226, vcc
	s_nop 0
	v_max_f32_dpp v17, v17, v17 row_mirror row_mask:0xf bank_mask:0xf
	v_cmp_eq_f32_e32 vcc, v9, v17
	v_cndmask_b32_e64 v15, v15, v17, s[16:17]
	v_max_f32_dpp v18, v12, v19 quad_perm:[1,0,3,2] row_mask:0xf bank_mask:0xf
	v_cndmask_b32_e32 v9, v9, v13, vcc
	s_nop 0
	v_max_f32_dpp v18, v18, v18 quad_perm:[2,3,0,1] row_mask:0xf bank_mask:0xf
	v_cndmask_b32_e32 v13, v13, v10, vcc
	s_nop 0
	v_max_f32_dpp v18, v18, v18 row_half_mirror row_mask:0xf bank_mask:0xf
	v_cndmask_b32_e32 v10, v10, v7, vcc
	v_cndmask_b32_e32 v7, v7, v226, vcc
	v_max_f32_dpp v18, v18, v18 row_mirror row_mask:0xf bank_mask:0xf
	v_cmp_eq_f32_e32 vcc, v12, v18
	v_cndmask_b32_e64 v16, v16, v18, s[16:17]
	v_max_f32_e32 v18, v9, v9
	v_max_f32_dpp v17, v9, v18 quad_perm:[1,0,3,2] row_mask:0xf bank_mask:0xf
	v_cndmask_b32_e32 v12, v12, v11, vcc
	v_max_f32_e32 v19, v12, v12
	v_max_f32_dpp v17, v17, v17 quad_perm:[2,3,0,1] row_mask:0xf bank_mask:0xf
	v_cndmask_b32_e32 v11, v11, v14, vcc
	v_cndmask_b32_e32 v14, v14, v8, vcc
	v_max_f32_dpp v17, v17, v17 row_half_mirror row_mask:0xf bank_mask:0xf
	v_cndmask_b32_e32 v8, v8, v226, vcc
	s_nop 0
	v_max_f32_dpp v17, v17, v17 row_mirror row_mask:0xf bank_mask:0xf
	v_cmp_eq_f32_e32 vcc, v9, v17
	s_nop 0
	v_max_f32_dpp v18, v12, v19 quad_perm:[1,0,3,2] row_mask:0xf bank_mask:0xf
	v_cndmask_b32_e32 v9, v9, v13, vcc
	v_cndmask_b32_e32 v13, v13, v10, vcc
	v_max_f32_dpp v18, v18, v18 quad_perm:[2,3,0,1] row_mask:0xf bank_mask:0xf
	v_cndmask_b32_e32 v7, v10, v7, vcc
	v_cndmask_b32_e64 v10, v15, v17, s[82:83]
	v_max_f32_dpp v18, v18, v18 row_half_mirror row_mask:0xf bank_mask:0xf
	v_mov_b32_e32 v19, v18
	s_nop 0
	s_nop 0
	v_mov_b32_dpp v19, v19 row_mirror row_mask:0xf bank_mask:0xf
	v_max_f32_e32 v19, v19, v19
	v_max_f32_e32 v18, v18, v19
	v_cmp_eq_f32_e32 vcc, v12, v18
	s_nop 1
	v_cndmask_b32_e32 v12, v12, v11, vcc
	v_cndmask_b32_e32 v11, v11, v14, vcc
	v_cndmask_b32_e32 v8, v14, v8, vcc
	v_cndmask_b32_e64 v14, v16, v18, s[82:83]
	v_max_f32_e32 v16, v9, v9
	v_max_f32_dpp v15, v9, v16 quad_perm:[1,0,3,2] row_mask:0xf bank_mask:0xf
	v_max_f32_e32 v17, v12, v12
	s_nop 0
	v_max_f32_dpp v15, v15, v15 quad_perm:[2,3,0,1] row_mask:0xf bank_mask:0xf
	s_nop 1
	v_max_f32_dpp v15, v15, v15 row_half_mirror row_mask:0xf bank_mask:0xf
	s_nop 1
	v_max_f32_dpp v15, v15, v15 row_mirror row_mask:0xf bank_mask:0xf
	v_cmp_eq_f32_e32 vcc, v9, v15
	v_cndmask_b32_e64 v10, v10, v15, s[84:85]
	v_max_f32_dpp v16, v12, v17 quad_perm:[1,0,3,2] row_mask:0xf bank_mask:0xf
	v_cndmask_b32_e32 v9, v9, v13, vcc
	v_cndmask_b32_e32 v7, v13, v7, vcc
	v_max_f32_dpp v16, v16, v16 quad_perm:[2,3,0,1] row_mask:0xf bank_mask:0xf
	s_nop 0
	s_nop 0
	v_max_f32_dpp v16, v16, v16 row_half_mirror row_mask:0xf bank_mask:0xf
	v_mov_b32_e32 v17, v16
	s_nop 1
	v_mov_b32_dpp v17, v17 row_mirror row_mask:0xf bank_mask:0xf
	v_max_f32_e32 v17, v17, v17
	v_max_f32_e32 v16, v16, v17
	v_cmp_eq_f32_e32 vcc, v12, v16
	s_nop 1
	v_cndmask_b32_e32 v12, v12, v11, vcc
	v_cndmask_b32_e32 v8, v11, v8, vcc
	v_cndmask_b32_e64 v11, v14, v16, s[84:85]
	v_max_f32_e32 v14, v9, v9
	v_max_f32_dpp v13, v9, v14 quad_perm:[1,0,3,2] row_mask:0xf bank_mask:0xf
	v_max_f32_e32 v15, v12, v12
	s_nop 0
	v_max_f32_dpp v13, v13, v13 quad_perm:[2,3,0,1] row_mask:0xf bank_mask:0xf
	s_nop 1
	v_max_f32_dpp v13, v13, v13 row_half_mirror row_mask:0xf bank_mask:0xf
	s_nop 1
	v_max_f32_dpp v13, v13, v13 row_mirror row_mask:0xf bank_mask:0xf
	v_cmp_eq_f32_e32 vcc, v9, v13
	s_nop 0
	v_max_f32_dpp v14, v12, v15 quad_perm:[1,0,3,2] row_mask:0xf bank_mask:0xf
	v_cndmask_b32_e32 v7, v9, v7, vcc
	v_cndmask_b32_e64 v9, v10, v13, s[86:87]
	v_max_f32_dpp v14, v14, v14 quad_perm:[2,3,0,1] row_mask:0xf bank_mask:0xf
	s_nop 1
	v_max_f32_dpp v14, v14, v14 row_half_mirror row_mask:0xf bank_mask:0xf
	s_nop 1
	v_max_f32_dpp v14, v14, v14 row_mirror row_mask:0xf bank_mask:0xf
	v_cndmask_b32_e64 v10, v11, v14, s[86:87]
	v_max_f32_e32 v11, v7, v7
	v_mov_b32_dpp v7, v7 quad_perm:[1,0,3,2] row_mask:0xf bank_mask:0xf
	v_max_f32_e32 v7, v7, v7
	v_max_f32_e32 v7, v11, v7
	v_cmp_eq_f32_e32 vcc, v12, v14
	s_nop 0
	v_max_f32_dpp v7, v7, v7 quad_perm:[2,3,0,1] row_mask:0xf bank_mask:0xf
	v_cndmask_b32_e32 v8, v12, v8, vcc
	s_nop 0
	v_max_f32_dpp v7, v7, v7 row_half_mirror row_mask:0xf bank_mask:0xf
	s_nop 1
	v_max_f32_dpp v7, v7, v7 row_mirror row_mask:0xf bank_mask:0xf
	v_max_f32_e32 v11, v8, v8
	v_mov_b32_dpp v8, v8 quad_perm:[1,0,3,2] row_mask:0xf bank_mask:0xf
	v_max_f32_e32 v8, v8, v8
	v_max_f32_e32 v8, v11, v8
	v_cndmask_b32_e64 v7, v9, v7, s[88:89]
	v_bitop3_b32 v9, v7, 63, v7 bitop3:0xc
	v_max_f32_dpp v8, v8, v8 quad_perm:[2,3,0,1] row_mask:0xf bank_mask:0xf
	v_lshl_add_u32 v9, v9, 2, s22
	ds_read_b32 v9, v9
	v_max_f32_dpp v8, v8, v8 row_half_mirror row_mask:0xf bank_mask:0xf
	v_max_f32_e32 v12, v7, v7
	s_nop 0
	v_max_f32_dpp v8, v8, v8 row_mirror row_mask:0xf bank_mask:0xf
	v_cndmask_b32_e64 v10, v10, v8, s[88:89]
	v_bitop3_b32 v8, v10, 63, v10 bitop3:0xc
	v_lshl_add_u32 v8, v8, 2, s22
	ds_read_b32 v11, v8
	s_waitcnt lgkmcnt(1)
; DEVI float shfll(float v, int src) { return __int_as_float(__builtin_amdgcn_ds_bpermute(src << 2, __float_as_int(v))); }
; DEVI int key_idx(float k) { return 127 - (int)(__float_as_uint(k) & 127u); }
; DEVI void peer_topk_phase(const Params& p, int layer, char* lds) {
;     ...
;       for (int ps = 0; ps < 2; ++ps) {
;         const int tok = w * 8 + ps * 4 + row4;
;         const int cs = key_idx(best[ps]), st_ = stair[cs & 63];
;         const int e1 = key_idx(shfll(key[ps * 2], row4 * 16 + (st_ & 15))), e2 = key_idx(shfll(key[ps * 2 + 1], row4 * 16 + ((st_ >> 8) & 15)));
;         const float mx = row16_max(best[ps]);
;         const float ex = __expf(best[ps] - mx);
;         const float sm = row16_sum(ex);
;         const size_t o = (size_t)(row0 + tok) * 128 + h * 16 + i16;
;         PIDX[o] = e1 * 128 + e2; PG[o] = ex / sm;
;       }
	v_and_or_b32 v8, v9, 15, v139
	v_lshrrev_b32_e32 v9, 8, v9
	v_and_or_b32 v9, v9, 15, v139
	v_lshlrev_b32_e32 v9, 2, v9
	ds_bpermute_b32 v6, v9, v6
	s_waitcnt lgkmcnt(0)
	v_and_b32_e32 v6, 0x7f, v6
	v_max_f32_dpp v9, v7, v12 quad_perm:[1,0,3,2] row_mask:0xf bank_mask:0xf
	s_nop 1
	v_max_f32_dpp v9, v9, v9 quad_perm:[2,3,0,1] row_mask:0xf bank_mask:0xf
	s_nop 1
	v_max_f32_dpp v9, v9, v9 row_half_mirror row_mask:0xf bank_mask:0xf
	s_nop 1
	v_max_f32_dpp v9, v9, v9 row_mirror row_mask:0xf bank_mask:0xf
	v_sub_f32_e32 v7, v7, v9
	v_mul_f32_e32 v7, 0x3fb8aa3b, v7
	v_exp_f32_e32 v12, v7
	v_lshlrev_b32_e32 v7, 2, v8
	ds_bpermute_b32 v7, v7, v3
	v_add_f32_dpp v3, v12, v12 quad_perm:[1,0,3,2] row_mask:0xf bank_mask:0xf bound_ctrl:1
	s_waitcnt lgkmcnt(0)
	v_lshlrev_b32_e32 v7, 7, v7
	v_add_f32_dpp v3, v3, v3 quad_perm:[2,3,0,1] row_mask:0xf bank_mask:0xf bound_ctrl:1
	v_and_b32_e32 v7, 0x3f80, v7
	v_bitop3_b32 v14, v6, s37, v7 bitop3:0x36
	v_add_f32_dpp v3, v3, v3 row_half_mirror row_mask:0xf bank_mask:0xf bound_ctrl:1
	s_nop 1
	v_add_f32_dpp v13, v3, v3 row_mirror row_mask:0xf bank_mask:0xf bound_ctrl:1
	v_ashrrev_i32_e32 v3, 31, v2
	v_lshlrev_b64 v[6:7], 9, v[2:3]
	v_div_scale_f32 v3, s[22:23], v13, v13, v12
	v_rcp_f32_e32 v15, v3
	v_or_b32_e32 v6, v6, v0
	v_lshl_add_u64 v[8:9], s[6:7], 0, v[6:7]
	global_store_dword v[8:9], v14, off
	v_fma_f32 v8, -v3, v15, 1.0
	v_fmac_f32_e32 v15, v8, v15
	v_div_scale_f32 v8, vcc, v12, v13, v12
	v_mul_f32_e32 v9, v8, v15
	v_fma_f32 v14, -v3, v9, v8
	v_fmac_f32_e32 v9, v14, v15
	v_fma_f32 v3, -v3, v9, v8
	v_div_fmas_f32 v3, v3, v15, v9
	v_div_fixup_f32 v3, v3, v13, v12
	v_lshl_add_u64 v[6:7], s[2:3], 0, v[6:7]
	global_store_dword v[6:7], v3, off
	v_lshrrev_b32_e32 v6, 8, v11
	v_and_or_b32 v6, v6, 15, v139
	v_lshlrev_b32_e32 v6, 2, v6
	ds_bpermute_b32 v5, v6, v5
	v_max_f32_e32 v7, v10, v10
	v_and_or_b32 v3, v11, 15, v139
	v_max_f32_dpp v6, v10, v7 quad_perm:[1,0,3,2] row_mask:0xf bank_mask:0xf
	v_lshlrev_b32_e32 v3, 2, v3
	ds_bpermute_b32 v4, v3, v4
	v_max_f32_dpp v6, v6, v6 quad_perm:[2,3,0,1] row_mask:0xf bank_mask:0xf
	v_or_b32_e32 v2, 4, v2
	s_waitcnt lgkmcnt(0)
	v_lshlrev_b32_e32 v4, 7, v4
	v_max_f32_dpp v6, v6, v6 row_half_mirror row_mask:0xf bank_mask:0xf
	v_and_b32_e32 v5, 0x7f, v5
	v_and_b32_e32 v4, 0x3f80, v4
	v_max_f32_dpp v6, v6, v6 row_mirror row_mask:0xf bank_mask:0xf
	v_sub_f32_e32 v6, v10, v6
	v_mul_f32_e32 v6, 0x3fb8aa3b, v6
	v_exp_f32_e32 v6, v6
	v_bitop3_b32 v8, v5, s37, v4 bitop3:0x36
	s_mov_b32 s37, s24
	v_add_f32_dpp v3, v6, v6 quad_perm:[1,0,3,2] row_mask:0xf bank_mask:0xf bound_ctrl:1
	s_nop 1
	v_add_f32_dpp v3, v3, v3 quad_perm:[2,3,0,1] row_mask:0xf bank_mask:0xf bound_ctrl:1
	s_nop 1
	v_add_f32_dpp v3, v3, v3 row_half_mirror row_mask:0xf bank_mask:0xf bound_ctrl:1
	s_nop 1
	v_add_f32_dpp v7, v3, v3 row_mirror row_mask:0xf bank_mask:0xf bound_ctrl:1
	v_div_scale_f32 v9, s[22:23], v7, v7, v6
	v_rcp_f32_e32 v10, v9
	v_ashrrev_i32_e32 v3, 31, v2
	v_lshlrev_b64 v[2:3], 9, v[2:3]
	v_or_b32_e32 v2, v2, v0
	v_fma_f32 v0, -v9, v10, 1.0
	v_lshl_add_u64 v[4:5], s[6:7], 0, v[2:3]
	v_fmac_f32_e32 v10, v0, v10
	v_div_scale_f32 v0, vcc, v6, v7, v6
	global_store_dword v[4:5], v8, off
	v_mul_f32_e32 v4, v0, v10
	v_fma_f32 v5, -v9, v4, v0
	v_fmac_f32_e32 v4, v5, v10
	v_fma_f32 v0, -v9, v4, v0
	v_div_fmas_f32 v0, v0, v10, v4
	v_div_fixup_f32 v0, v0, v7, v6
	v_lshl_add_u64 v[2:3], s[2:3], 0, v[2:3]
	s_and_b64 vcc, exec, s[34:35]
	global_store_dword v[2:3], v0, off
	s_barrier
	s_cbranch_vccnz .LBB0_211

; DEVI bf16_t f2bf(float x) { return (bf16_t)(cvtpk(x, x) & 0xffffu); }
; DEVI float bf2f(bf16_t u) { return __uint_as_float(((unsigned)u) << 16); }
; DEVI void lru_coef_phase(const Params& p, char* lds) {
;     ...
;     {
;       const int c = tid & 127, rg = tid >> 7, ch = blk * 128 + c;
;       const float w0 = p.in[I_LCW][ch], w1 = p.in[I_LCW][1024 + ch], w2 = p.in[I_LCW][2048 + ch], w3 = p.in[I_LCW][3072 + ch], cb = p.in[I_LCB][ch];
;       const int rs = r0 + rg * 16;
;       auto ld = [&](int row) -> float { return (row >= seg0 && row < seg1) ? bf2f(GX[(size_t)row * 2048 + 1024 + ch]) : 0.f; };
;       float xm2 = ld(rs - 2), xm1 = ld(rs - 1), x0 = ld(rs);
; #pragma unroll
;       for (int t = 0; t < 16; ++t) {
;         const float xp1 = ld(rs + t + 1);
;         const float v = w0 * xm2 + w1 * xm1 + w2 * x0 + w3 * xp1 + cb;
;         const int lr = rg * 16 + t;
;         XR[lr * 128 + c] = v;
;         *(bf16_t*)(AT + lr * 256 + ((((c >> 3) ^ (lr & 15)) << 4) | ((c & 7) << 1))) = f2bf(v);
;         xm2 = xm1; xm1 = x0; x0 = xp1;
;       }
;     }
.LBB0_1153:
	s_lshl_b32 s0, s34, 3
	s_and_b32 s2, s0, 0xffffffc0
	s_and_b32 s3, s0, 0xffffc000
	s_and_b32 s0, s0, 0xffffff00
	s_and_b32 s1, s34, 7
	s_add_i32 s22, s3, 0x4000
	s_add_i32 s23, s0, 0x100
	s_cmp_lt_i32 s2, 0x8000
	s_cselect_b32 s3, s3, s0
	s_cselect_b32 s35, s22, s23
	s_lshl_b32 s0, s1, 7
	v_or_b32_e32 v6, s0, v83
	v_readlane_b32 s60, v255, 10
	v_lshlrev_b32_e32 v0, 2, v6
	v_readlane_b32 s62, v255, 12
	v_readlane_b32 s63, v255, 13
	v_readlane_b32 s64, v255, 14
	v_readlane_b32 s65, v255, 15
	v_lshl_add_u64 v[2:3], s[62:63], 0, v[0:1]
	v_add_co_u32_e32 v4, vcc, s51, v2
	s_nop 0
	global_load_dword v8, v0, s[62:63]
	v_addc_co_u32_e32 v5, vcc, 0, v3, vcc
	global_load_dword v9, v[4:5], off
	v_add_co_u32_e32 v4, vcc, 0x2000, v2
	v_mov_b32_e32 v12, 0
	s_nop 0
	v_addc_co_u32_e32 v5, vcc, 0, v3, vcc
	v_add_co_u32_e32 v2, vcc, 0x3000, v2
	global_load_dword v10, v[4:5], off
	s_nop 0
	v_addc_co_u32_e32 v3, vcc, 0, v3, vcc
	global_load_dword v11, v[2:3], off
	s_nop 0
	global_load_dword v0, v0, s[64:65]
	v_add_u32_e32 v4, s2, v118
	v_lshlrev_b32_e32 v2, 1, v6
	v_readfirstlane_b32 s22, v118
	v_lshl_add_u32 v5, v4, 12, v2
	v_add_u32_e32 v5, 0xfffff000, v5
	s_add_i32 s22, s2, s22
	v_mov_b32_e32 v20, 0
	v_mov_b32_e32 v21, 0
	v_mov_b32_e32 v38, 0
	s_cmp_le_i32 s22, s3
	s_cbranch_scc1 .Llcoef_a
	global_load_ushort v20, v5, s[12:13] offset:-2048
	global_load_ushort v21, v5, s[12:13] offset:2048
.Llcoef_a:
	v_add_u32_e32 v5, 0x2000, v5
	global_load_ushort v22, v5, s[12:13] offset:-2048
	global_load_ushort v23, v5, s[12:13] offset:2048
	v_add_u32_e32 v5, 0x2000, v5
	global_load_ushort v24, v5, s[12:13] offset:-2048
	global_load_ushort v25, v5, s[12:13] offset:2048
	v_add_u32_e32 v5, 0x2000, v5
	global_load_ushort v26, v5, s[12:13] offset:-2048
	global_load_ushort v27, v5, s[12:13] offset:2048
	v_add_u32_e32 v5, 0x2000, v5
	global_load_ushort v28, v5, s[12:13] offset:-2048
	global_load_ushort v29, v5, s[12:13] offset:2048
	v_add_u32_e32 v5, 0x2000, v5
	global_load_ushort v30, v5, s[12:13] offset:-2048
	global_load_ushort v31, v5, s[12:13] offset:2048
	v_add_u32_e32 v5, 0x2000, v5
	global_load_ushort v32, v5, s[12:13] offset:-2048
	global_load_ushort v33, v5, s[12:13] offset:2048
	v_add_u32_e32 v5, 0x2000, v5
	global_load_ushort v34, v5, s[12:13] offset:-2048
	global_load_ushort v35, v5, s[12:13] offset:2048
	v_add_u32_e32 v5, 0x2000, v5
	global_load_ushort v36, v5, s[12:13] offset:-2048
	global_load_ushort v37, v5, s[12:13] offset:2048
	v_add_u32_e32 v5, 0x2000, v5
	s_add_i32 s23, s22, 16
	s_cmp_ge_i32 s23, s35
	s_cbranch_scc1 .Llcoef_b
	global_load_ushort v38, v5, s[12:13] offset:-2048
.Llcoef_b:
	s_waitcnt vmcnt(0)
	v_lshlrev_b32_e32 v20, 16, v20
	v_lshlrev_b32_e32 v21, 16, v21
	v_lshlrev_b32_e32 v22, 16, v22
	v_lshlrev_b32_e32 v23, 16, v23
	v_lshlrev_b32_e32 v24, 16, v24
	v_lshlrev_b32_e32 v25, 16, v25
	v_lshlrev_b32_e32 v26, 16, v26
	v_lshlrev_b32_e32 v27, 16, v27
	v_lshlrev_b32_e32 v28, 16, v28
	v_lshlrev_b32_e32 v29, 16, v29
	v_lshlrev_b32_e32 v30, 16, v30
	v_lshlrev_b32_e32 v31, 16, v31
	v_lshlrev_b32_e32 v32, 16, v32
	v_lshlrev_b32_e32 v33, 16, v33
	v_lshlrev_b32_e32 v34, 16, v34
	v_lshlrev_b32_e32 v35, 16, v35
	v_lshlrev_b32_e32 v36, 16, v36
	v_lshlrev_b32_e32 v37, 16, v37
	v_lshlrev_b32_e32 v38, 16, v38
	v_mul_f32_e32 v3, v9, v21
	v_fmac_f32_e32 v3, v8, v20
	v_fmac_f32_e32 v3, v10, v22
	v_fmac_f32_e32 v3, v11, v23
	v_add_f32_e32 v3, v0, v3
	ds_write_b32 v123, v3
	v_cvt_pk_bf16_f32 v3, v3, v3
	ds_write_b16 v124, v3 offset:32768
	v_mul_f32_e32 v3, v9, v22
	v_fmac_f32_e32 v3, v8, v21
	v_fmac_f32_e32 v3, v10, v23
	v_fmac_f32_e32 v3, v11, v24
	v_add_f32_e32 v3, v0, v3
	ds_write_b32 v125, v3
	v_cvt_pk_bf16_f32 v3, v3, v3
	ds_write_b16 v126, v3 offset:32768
	v_mul_f32_e32 v3, v9, v23
	v_fmac_f32_e32 v3, v8, v22
	v_fmac_f32_e32 v3, v10, v24
	v_fmac_f32_e32 v3, v11, v25
	v_add_f32_e32 v3, v0, v3
	ds_write_b32 v127, v3
	v_cvt_pk_bf16_f32 v3, v3, v3
	ds_write_b16 v128, v3 offset:32768
	v_mul_f32_e32 v3, v9, v24
	v_fmac_f32_e32 v3, v8, v23
	v_fmac_f32_e32 v3, v10, v25
	v_fmac_f32_e32 v3, v11, v26
	v_add_f32_e32 v3, v0, v3
	ds_write_b32 v129, v3
	v_cvt_pk_bf16_f32 v3, v3, v3
	ds_write_b16 v130, v3 offset:32768
	v_mul_f32_e32 v3, v9, v25
	v_fmac_f32_e32 v3, v8, v24
	v_fmac_f32_e32 v3, v10, v26
	v_fmac_f32_e32 v3, v11, v27
	v_add_f32_e32 v3, v0, v3
	ds_write_b32 v131, v3
	v_cvt_pk_bf16_f32 v3, v3, v3
	ds_write_b16 v132, v3 offset:32768
	v_mul_f32_e32 v3, v9, v26
	v_fmac_f32_e32 v3, v8, v25
	v_fmac_f32_e32 v3, v10, v27
	v_fmac_f32_e32 v3, v11, v28
	v_add_f32_e32 v3, v0, v3
	ds_write_b32 v133, v3
	v_cvt_pk_bf16_f32 v3, v3, v3
	ds_write_b16 v134, v3 offset:32768
	v_mul_f32_e32 v3, v9, v27
	v_fmac_f32_e32 v3, v8, v26
	v_fmac_f32_e32 v3, v10, v28
	v_fmac_f32_e32 v3, v11, v29
	v_add_f32_e32 v3, v0, v3
	ds_write_b32 v135, v3
	v_cvt_pk_bf16_f32 v3, v3, v3
	ds_write_b16 v136, v3 offset:32768
	v_mul_f32_e32 v3, v9, v28
	v_fmac_f32_e32 v3, v8, v27
	v_fmac_f32_e32 v3, v10, v29
	v_fmac_f32_e32 v3, v11, v30
	v_add_f32_e32 v3, v0, v3
	ds_write_b32 v137, v3
	v_cvt_pk_bf16_f32 v3, v3, v3
	ds_write_b16 v138, v3 offset:32768
	v_mul_f32_e32 v3, v9, v29
	v_fmac_f32_e32 v3, v8, v28
	v_fmac_f32_e32 v3, v10, v30
	v_fmac_f32_e32 v3, v11, v31
	v_add_f32_e32 v3, v0, v3
	ds_write_b32 v139, v3
	v_cvt_pk_bf16_f32 v3, v3, v3
	ds_write_b16 v140, v3 offset:32768
	v_mul_f32_e32 v3, v9, v30
	v_fmac_f32_e32 v3, v8, v29
	v_fmac_f32_e32 v3, v10, v31
	v_fmac_f32_e32 v3, v11, v32
	v_add_f32_e32 v3, v0, v3
	ds_write_b32 v141, v3
	v_cvt_pk_bf16_f32 v3, v3, v3
	ds_write_b16 v142, v3 offset:32768
	v_mul_f32_e32 v3, v9, v31
	v_fmac_f32_e32 v3, v8, v30
	v_fmac_f32_e32 v3, v10, v32
	v_fmac_f32_e32 v3, v11, v33
; DEVI bf16_t f2bf(float x) { return (bf16_t)(cvtpk(x, x) & 0xffffu); }
; DEVI void lru_coef_phase(const Params& p, char* lds) {
;     ...
;       for (int t = 0; t < 16; ++t) {
;         const float xp1 = ld(rs + t + 1);
;         const float v = w0 * xm2 + w1 * xm1 + w2 * x0 + w3 * xp1 + cb;
;         const int lr = rg * 16 + t;
;         XR[lr * 128 + c] = v;
;         *(bf16_t*)(AT + lr * 256 + ((((c >> 3) ^ (lr & 15)) << 4) | ((c & 7) << 1))) = f2bf(v);
;         xm2 = xm1; xm1 = x0; x0 = xp1;
;       }
;     }
;     ...
;     const int dir = w >> 2, rb = (w >> 1) & 1, chh = w & 1;
;     f32x16 ar[2], ai[2];
; #pragma unroll
;     for (int nb = 0; nb < 2; ++nb) { ar[nb] = f32x16{}; ai[nb] = f32x16{}; }
;     const bf16_t* wr = WT + WT_LRG + ((size_t)(dir * 8 + blk) * 128 + chh * 64 + r32) * 128 + hi * 8;
;     const bf16_t* wg = WT + WT_LIG + ((size_t)(dir * 8 + blk) * 128 + chh * 64 + r32) * 128 + hi * 8;
; #pragma unroll
;     for (int s = 0; s < 8; ++s) {
;       const int lr = rb * 32 + r32;
;       const bf16x8 af = *(const bf16x8*)(AT + lr * 256 + (((s * 2 + hi) ^ (lr & 15)) << 4));
; #pragma unroll
;       for (int nb = 0; nb < 2; ++nb) {
;         const bf16x8 b1 = *(const bf16x8*)(wr + nb * 32 * 128 + s * 16);
;         const bf16x8 b2 = *(const bf16x8*)(wg + nb * 32 * 128 + s * 16);
;         ar[nb] = __builtin_amdgcn_mfma_f32_32x32x16_bf16(af, b1, ar[nb], 0, 0, 0);
;         ai[nb] = __builtin_amdgcn_mfma_f32_32x32x16_bf16(af, b2, ai[nb], 0, 0, 0);
;       }
;     }
	v_add_f32_e32 v3, v0, v3
	ds_write_b32 v143, v3
	v_cvt_pk_bf16_f32 v3, v3, v3
	ds_write_b16 v144, v3 offset:32768
	v_mul_f32_e32 v3, v9, v32
	v_fmac_f32_e32 v3, v8, v31
	v_fmac_f32_e32 v3, v10, v33
	v_fmac_f32_e32 v3, v11, v34
	v_add_f32_e32 v3, v0, v3
	ds_write_b32 v145, v3
	v_cvt_pk_bf16_f32 v3, v3, v3
	ds_write_b16 v146, v3 offset:32768
	v_mul_f32_e32 v3, v9, v33
	v_fmac_f32_e32 v3, v8, v32
	v_fmac_f32_e32 v3, v10, v34
	v_fmac_f32_e32 v3, v11, v35
	v_add_f32_e32 v3, v0, v3
	ds_write_b32 v147, v3
	v_cvt_pk_bf16_f32 v3, v3, v3
	ds_write_b16 v148, v3 offset:32768
	v_mul_f32_e32 v3, v9, v34
	v_fmac_f32_e32 v3, v8, v33
	v_fmac_f32_e32 v3, v10, v35
	v_fmac_f32_e32 v3, v11, v36
	v_add_f32_e32 v3, v0, v3
	ds_write_b32 v149, v3
	v_cvt_pk_bf16_f32 v3, v3, v3
	ds_write_b16 v150, v3 offset:32768
	v_mul_f32_e32 v3, v9, v35
	v_fmac_f32_e32 v3, v8, v34
	v_fmac_f32_e32 v3, v10, v36
	v_fmac_f32_e32 v3, v11, v37
	v_add_f32_e32 v3, v0, v3
	ds_write_b32 v151, v3
	v_cvt_pk_bf16_f32 v3, v3, v3
	ds_write_b16 v152, v3 offset:32768
	v_mul_f32_e32 v3, v9, v36
	v_fmac_f32_e32 v3, v8, v35
	v_fmac_f32_e32 v3, v10, v37
	v_fmac_f32_e32 v3, v11, v38
	v_add_f32_e32 v3, v0, v3
	ds_write_b32 v153, v3
	v_cvt_pk_bf16_f32 v3, v3, v3
	ds_write_b16 v154, v3 offset:32768
	v_readlane_b32 s61, v255, 11
	v_readlane_b32 s66, v255, 16
	v_readlane_b32 s67, v255, 17
	v_readlane_b32 s68, v255, 18
	v_readlane_b32 s69, v255, 19
	v_readlane_b32 s70, v255, 20
	v_readlane_b32 s71, v255, 21
	v_readlane_b32 s72, v255, 22
	v_readlane_b32 s73, v255, 23
	v_readlane_b32 s74, v255, 24
	v_readlane_b32 s75, v255, 25
	v_or_b32_e32 v2, s1, v119
	v_ashrrev_i32_e32 v3, 31, v2
	v_lshlrev_b64 v[2:3], 15, v[2:3]
	v_lshl_or_b32 v2, v82, 1, v2
	v_lshl_add_u64 v[98:99], v[66:67], 0, v[2:3]
	s_waitcnt lgkmcnt(0)
	s_barrier
	v_lshl_add_u64 v[100:101], v[68:69], 0, v[2:3]
	ds_read_b128 v[2:5], v155 offset:32768
	global_load_dwordx4 v[6:9], v[98:99], off
	global_load_dwordx4 v[10:13], v[100:101], off
	v_add_co_u32_e32 v102, vcc, s52, v98
	ds_read_b128 v[86:89], v156 offset:32768
	s_nop 0
	v_addc_co_u32_e32 v103, vcc, 0, v99, vcc
	v_add_co_u32_e32 v104, vcc, s52, v100
	v_or_b32_e32 v116, s0, v121
	s_nop 0
	v_addc_co_u32_e32 v105, vcc, 0, v101, vcc
	v_readlane_b32 s60, v255, 10
	v_readlane_b32 s68, v255, 18
	v_readlane_b32 s69, v255, 19
	v_readlane_b32 s72, v255, 22
	v_readlane_b32 s73, v255, 23
	v_readlane_b32 s74, v255, 24
	v_readlane_b32 s75, v255, 25
	v_ashrrev_i32_e32 v117, 31, v116
	v_readlane_b32 s61, v255, 11
	v_readlane_b32 s62, v255, 12
	v_readlane_b32 s63, v255, 13
	v_readlane_b32 s64, v255, 14
	v_readlane_b32 s65, v255, 15
	v_readlane_b32 s66, v255, 16
	v_readlane_b32 s67, v255, 17
	v_readlane_b32 s70, v255, 20
	v_readlane_b32 s71, v255, 21
	s_waitcnt vmcnt(1) lgkmcnt(1)
	v_mfma_f32_32x32x16_bf16 v[50:65], v[2:5], v[6:9], 0
	global_load_dwordx4 v[6:9], v[102:103], off
	s_waitcnt vmcnt(1)
	v_mfma_f32_32x32x16_bf16 v[18:33], v[2:5], v[10:13], 0
	global_load_dwordx4 v[10:13], v[104:105], off
	global_load_dwordx4 v[90:93], v[98:99], off offset:32
	global_load_dwordx4 v[94:97], v[100:101], off offset:32
	s_waitcnt vmcnt(1) lgkmcnt(0)
	v_mfma_f32_32x32x16_bf16 v[50:65], v[86:89], v[90:93], v[50:65]
	s_waitcnt vmcnt(0)
	v_mfma_f32_32x32x16_bf16 v[18:33], v[86:89], v[94:97], v[18:33]
	global_load_dwordx4 v[90:93], v[102:103], off offset:32
	global_load_dwordx4 v[94:97], v[104:105], off offset:32
	v_mfma_f32_32x32x16_bf16 v[34:49], v[2:5], v[6:9], 0
	v_mfma_f32_32x32x16_bf16 v[2:17], v[2:5], v[10:13], 0
	s_waitcnt vmcnt(1)
	v_mfma_f32_32x32x16_bf16 v[34:49], v[86:89], v[90:93], v[34:49]
	s_waitcnt vmcnt(0)
	v_mfma_f32_32x32x16_bf16 v[2:17], v[86:89], v[94:97], v[2:17]
	ds_read_b128 v[86:89], v157 offset:32768
	global_load_dwordx4 v[90:93], v[98:99], off offset:64
	global_load_dwordx4 v[94:97], v[100:101], off offset:64
	s_waitcnt vmcnt(1) lgkmcnt(0)
	v_mfma_f32_32x32x16_bf16 v[50:65], v[86:89], v[90:93], v[50:65]
	s_waitcnt vmcnt(0)
	v_mfma_f32_32x32x16_bf16 v[18:33], v[86:89], v[94:97], v[18:33]
	global_load_dwordx4 v[90:93], v[102:103], off offset:64
	global_load_dwordx4 v[94:97], v[104:105], off offset:64
	s_waitcnt vmcnt(1)
	v_mfma_f32_32x32x16_bf16 v[34:49], v[86:89], v[90:93], v[34:49]
	s_waitcnt vmcnt(0)
	v_mfma_f32_32x32x16_bf16 v[2:17], v[86:89], v[94:97], v[2:17]
	ds_read_b128 v[86:89], v158 offset:32768
	global_load_dwordx4 v[90:93], v[98:99], off offset:96
	global_load_dwordx4 v[94:97], v[100:101], off offset:96
	s_waitcnt vmcnt(1) lgkmcnt(0)
	v_mfma_f32_32x32x16_bf16 v[50:65], v[86:89], v[90:93], v[50:65]
	s_waitcnt vmcnt(0)
	v_mfma_f32_32x32x16_bf16 v[18:33], v[86:89], v[94:97], v[18:33]
	global_load_dwordx4 v[90:93], v[102:103], off offset:96
	global_load_dwordx4 v[94:97], v[104:105], off offset:96
	s_waitcnt vmcnt(1)
	v_mfma_f32_32x32x16_bf16 v[34:49], v[86:89], v[90:93], v[34:49]
	s_waitcnt vmcnt(0)
	v_mfma_f32_32x32x16_bf16 v[2:17], v[86:89], v[94:97], v[2:17]
	ds_read_b128 v[86:89], v159 offset:32768
	global_load_dwordx4 v[90:93], v[98:99], off offset:128
	global_load_dwordx4 v[94:97], v[100:101], off offset:128
	s_waitcnt vmcnt(1) lgkmcnt(0)
	v_mfma_f32_32x32x16_bf16 v[50:65], v[86:89], v[90:93], v[50:65]
	s_waitcnt vmcnt(0)
	v_mfma_f32_32x32x16_bf16 v[18:33], v[86:89], v[94:97], v[18:33]
	global_load_dwordx4 v[90:93], v[102:103], off offset:128
	global_load_dwordx4 v[94:97], v[104:105], off offset:128
	s_waitcnt vmcnt(1)
	v_mfma_f32_32x32x16_bf16 v[34:49], v[86:89], v[90:93], v[34:49]
	s_waitcnt vmcnt(0)
	v_mfma_f32_32x32x16_bf16 v[2:17], v[86:89], v[94:97], v[2:17]
	ds_read_b128 v[86:89], v160 offset:32768
	global_load_dwordx4 v[90:93], v[98:99], off offset:160
	global_load_dwordx4 v[94:97], v[100:101], off offset:160
	s_waitcnt vmcnt(1) lgkmcnt(0)
; DEVI void lru_coef_phase(const Params& p, char* lds) {
;     ...
;     for (int s = 0; s < 8; ++s) {
;       const int lr = rb * 32 + r32;
;       const bf16x8 af = *(const bf16x8*)(AT + lr * 256 + (((s * 2 + hi) ^ (lr & 15)) << 4));
; #pragma unroll
;       for (int nb = 0; nb < 2; ++nb) {
;         const bf16x8 b1 = *(const bf16x8*)(wr + nb * 32 * 128 + s * 16);
;         const bf16x8 b2 = *(const bf16x8*)(wg + nb * 32 * 128 + s * 16);
;         ar[nb] = __builtin_amdgcn_mfma_f32_32x32x16_bf16(af, b1, ar[nb], 0, 0, 0);
;         ai[nb] = __builtin_amdgcn_mfma_f32_32x32x16_bf16(af, b2, ai[nb], 0, 0, 0);
;       }
;     }
;     f32x16 tla[2], tbb[2];
; #pragma unroll
;     for (int nb = 0; nb < 2; ++nb) {
;       const int col = chh * 64 + nb * 32 + r32, ch = blk * 128 + col;
;       const float brg = p.in[I_LBRG][dir * 1024 + ch], big = p.in[I_LBIG][dir * 1024 + ch];
;       const float sp = log1pf(__expf(-p.in[I_LLAM][dir * 1024 + ch]));
	v_mfma_f32_32x32x16_bf16 v[50:65], v[86:89], v[90:93], v[50:65]
	s_waitcnt vmcnt(0)
	v_mfma_f32_32x32x16_bf16 v[18:33], v[86:89], v[94:97], v[18:33]
	global_load_dwordx4 v[90:93], v[102:103], off offset:160
	global_load_dwordx4 v[94:97], v[104:105], off offset:160
	s_waitcnt vmcnt(1)
	v_mfma_f32_32x32x16_bf16 v[34:49], v[86:89], v[90:93], v[34:49]
	s_waitcnt vmcnt(0)
	v_mfma_f32_32x32x16_bf16 v[2:17], v[86:89], v[94:97], v[2:17]
	ds_read_b128 v[86:89], v161 offset:32768
	global_load_dwordx4 v[90:93], v[98:99], off offset:192
	global_load_dwordx4 v[94:97], v[100:101], off offset:192
	s_waitcnt vmcnt(1) lgkmcnt(0)
	v_mfma_f32_32x32x16_bf16 v[50:65], v[86:89], v[90:93], v[50:65]
	s_waitcnt vmcnt(0)
	v_mfma_f32_32x32x16_bf16 v[18:33], v[86:89], v[94:97], v[18:33]
	global_load_dwordx4 v[90:93], v[102:103], off offset:192
	global_load_dwordx4 v[94:97], v[104:105], off offset:192
	s_waitcnt vmcnt(1)
	v_mfma_f32_32x32x16_bf16 v[34:49], v[86:89], v[90:93], v[34:49]
	s_waitcnt vmcnt(0)
	v_mfma_f32_32x32x16_bf16 v[2:17], v[86:89], v[94:97], v[2:17]
	ds_read_b128 v[86:89], v162 offset:32768
	global_load_dwordx4 v[90:93], v[98:99], off offset:224
	global_load_dwordx4 v[94:97], v[100:101], off offset:224
	s_waitcnt vmcnt(1) lgkmcnt(0)
	v_mfma_f32_32x32x16_bf16 v[50:65], v[86:89], v[90:93], v[50:65]
	s_waitcnt vmcnt(0)
	v_mfma_f32_32x32x16_bf16 v[18:33], v[86:89], v[94:97], v[18:33]
	global_load_dwordx4 v[90:93], v[102:103], off offset:224
	global_load_dwordx4 v[94:97], v[104:105], off offset:224
	ds_read2_b32 v[112:113], v122 offset1:32
	ds_read2_b32 v[114:115], v122 offset0:128 offset1:160
	s_waitcnt vmcnt(1)
	v_mfma_f32_32x32x16_bf16 v[34:49], v[86:89], v[90:93], v[34:49]
	s_waitcnt vmcnt(0)
	v_mfma_f32_32x32x16_bf16 v[2:17], v[86:89], v[94:97], v[2:17]
	v_or_b32_e32 v86, v116, v70
	v_ashrrev_i32_e32 v87, 31, v86
	v_lshlrev_b64 v[86:87], 2, v[86:87]
	v_lshl_add_u64 v[88:89], s[68:69], 0, v[86:87]
	global_load_dword v169, v[88:89], off
	v_lshl_add_u64 v[88:89], s[72:73], 0, v[86:87]
	v_lshl_add_u64 v[86:87], s[74:75], 0, v[86:87]
	global_load_dword v0, v[86:87], off
	global_load_dword v168, v[88:89], off
	v_lshl_add_u64 v[116:117], v[116:117], 0, v[70:71]
	v_lshlrev_b64 v[170:171], 2, v[116:117]
	v_lshl_add_u64 v[116:117], s[68:69], 0, v[170:171]
	v_lshl_add_u64 v[172:173], s[72:73], 0, v[170:171]
	v_lshl_add_u64 v[170:171], s[74:75], 0, v[170:171]
	s_waitcnt vmcnt(1)
; DEVI float sigmoidf_(float x) { return __builtin_amdgcn_rcpf(1.f + __expf(-x)); }
; DEVI int crow(int r, int hi) { return (r & 3) + 8 * (r >> 2) + 4 * hi; }
; DEVI void lru_coef_phase(const Params& p, char* lds) {
;     ...
;       const float brg = p.in[I_LBRG][dir * 1024 + ch], big = p.in[I_LBIG][dir * 1024 + ch];
;       const float sp = log1pf(__expf(-p.in[I_LLAM][dir * 1024 + ch]));
; #pragma unroll
;       for (int r = 0; r < 16; ++r) {
;         const int lr = rb * 32 + crow(r, hi);
;         const float xr = XR[lr * 128 + col];
;         const float rg_ = sigmoidf_(ar[nb][r] + brg), ig_ = sigmoidf_(ai[nb][r] + big);
;         const float la = -8.f * rg_ * sp;
;         tla[nb][r] = la;
;         const float x2 = 2.f * la;
;         const float om = -x2 * fmaf(x2, fmaf(x2, fmaf(x2, fmaf(x2, 1.f / 120.f, 1.f / 24.f), 1.f / 6.f), 0.5f), 1.f);
;         tbb[nb][r] = __builtin_amdgcn_sqrtf(fmaxf(om, 0.f)) * ig_ * xr;
;       }
;     }
;     {
;       bf16_t* d1 = LA + ((size_t)dir * MT + r0 + rb * 32) * 1024; bf16_t* d2 = BB + ((size_t)dir * MT + r0 + rb * 32) * 1024;
;       char* slice = lds + 49152 + w * 4096;
;       store2_bf16(tla[0], tla[1], slice, lane, blk * 128 + chh * 64, [=](int rr) { return d1 + (size_t)rr * 1024; });
;       store2_bf16(tbb[0], tbb[1], slice, lane, blk * 128 + chh * 64, [=](int rr) { return d2 + (size_t)rr * 1024; });
	v_mul_f32_e32 v0, 0xbfb8aa3b, v0
	v_exp_f32_e32 v0, v0
	s_nop 0
	v_add_f32_e32 v85, 1.0, v0
	v_add_f32_e32 v86, -1.0, v85
	v_sub_f32_e32 v87, v86, v85
	v_add_f32_e32 v87, 1.0, v87
	v_sub_f32_e32 v86, v0, v86
	v_add_f32_e32 v88, v86, v87
	v_frexp_mant_f32_e32 v86, v85
	v_cmp_gt_f32_e32 vcc, s54, v86
	v_cvt_f64_f32_e32 v[86:87], v85
	v_frexp_exp_i32_f64_e32 v86, v[86:87]
	v_subbrev_co_u32_e32 v86, vcc, 0, v86, vcc
	v_sub_u32_e32 v87, 0, v86
	v_ldexp_f32 v85, v85, v87
	v_ldexp_f32 v87, v88, v87
	v_add_f32_e32 v88, -1.0, v85
	v_add_f32_e32 v89, 1.0, v88
	v_sub_f32_e32 v89, v85, v89
	v_add_f32_e32 v89, v87, v89
	v_add_f32_e32 v90, v88, v89
	v_sub_f32_e32 v88, v90, v88
	v_sub_f32_e32 v88, v89, v88
	v_add_f32_e32 v89, 1.0, v85
	v_add_f32_e32 v91, -1.0, v89
	v_sub_f32_e32 v85, v85, v91
	v_add_f32_e32 v85, v87, v85
	v_add_f32_e32 v87, v89, v85
	v_sub_f32_e32 v89, v87, v89
	v_sub_f32_e32 v85, v85, v89
	v_rcp_f32_e32 v89, v87
	v_cvt_f32_i32_e32 v86, v86
	v_cmp_neq_f32_e32 vcc, s53, v0
	v_mul_f32_e32 v91, v90, v89
	v_mul_f32_e32 v92, v87, v91
	v_fma_f32 v93, v91, v87, -v92
	v_fmac_f32_e32 v93, v91, v85
	v_add_f32_e32 v94, v92, v93
	v_sub_f32_e32 v95, v90, v94
	v_sub_f32_e32 v90, v90, v95
	v_sub_f32_e32 v92, v94, v92
	v_sub_f32_e32 v90, v90, v94
	v_add_f32_e32 v88, v88, v90
	v_sub_f32_e32 v90, v92, v93
	v_add_f32_e32 v88, v90, v88
	v_add_f32_e32 v90, v95, v88
	v_mul_f32_e32 v92, v89, v90
	v_mul_f32_e32 v93, v87, v92
	v_fma_f32 v87, v92, v87, -v93
	v_fmac_f32_e32 v87, v92, v85
	v_sub_f32_e32 v85, v95, v90
	v_add_f32_e32 v85, v88, v85
	v_add_f32_e32 v88, v93, v87
	v_sub_f32_e32 v94, v90, v88
	v_sub_f32_e32 v90, v90, v94
	v_sub_f32_e32 v93, v88, v93
	v_sub_f32_e32 v88, v90, v88
	v_add_f32_e32 v85, v85, v88
	v_sub_f32_e32 v87, v93, v87
	v_add_f32_e32 v85, v87, v85
	v_add_f32_e32 v87, v91, v92
	v_add_f32_e32 v85, v94, v85
	v_sub_f32_e32 v88, v87, v91
	v_mul_f32_e32 v85, v89, v85
	v_sub_f32_e32 v88, v92, v88
	v_add_f32_e32 v85, v88, v85
	v_mul_f32_e32 v91, 0x3f317218, v86
	v_add_f32_e32 v88, v87, v85
	v_fma_f32 v92, v86, s55, -v91
	v_mul_f32_e32 v89, v88, v88
	v_fmac_f32_e32 v92, 0xb102e308, v86
	v_sub_f32_e32 v86, v88, v87
	v_fmamk_f32 v90, v89, 0x3e9b6dac, v218
	v_sub_f32_e32 v85, v85, v86
	v_add_f32_e32 v86, v91, v92
	v_fmaak_f32 v90, v89, v90, 0x3f2aaada
	v_sub_f32_e32 v87, v86, v91
	v_ldexp_f32 v91, v88, 1
	v_mul_f32_e32 v88, v88, v89
	v_mul_f32_e32 v88, v88, v90
	v_add_f32_e32 v89, v91, v88
	v_sub_f32_e32 v90, v89, v91
	v_ldexp_f32 v85, v85, 1
	v_sub_f32_e32 v88, v88, v90
	v_add_f32_e32 v85, v85, v88
	v_add_f32_e32 v88, v89, v85
	v_sub_f32_e32 v89, v88, v89
	v_sub_f32_e32 v85, v85, v89
	v_add_f32_e32 v89, v86, v88
	v_sub_f32_e32 v90, v89, v86
	v_sub_f32_e32 v91, v89, v90
	v_sub_f32_e32 v87, v92, v87
	v_sub_f32_e32 v86, v86, v91
	v_sub_f32_e32 v88, v88, v90
	v_add_f32_e32 v86, v88, v86
	v_add_f32_e32 v88, v87, v85
	v_sub_f32_e32 v90, v88, v87
	v_sub_f32_e32 v91, v88, v90
	v_sub_f32_e32 v87, v87, v91
	v_sub_f32_e32 v85, v85, v90
	v_add_f32_e32 v86, v88, v86
	v_add_f32_e32 v85, v85, v87
	v_add_f32_e32 v87, v89, v86
	v_sub_f32_e32 v88, v87, v89
	v_sub_f32_e32 v86, v86, v88
	v_add_f32_e32 v85, v85, v86
	v_add_f32_e32 v85, v87, v85
	v_cndmask_b32_e32 v85, v224, v85, vcc
	v_cmp_ngt_f32_e32 vcc, -1.0, v0
	s_nop 1
	v_cndmask_b32_e32 v85, v228, v85, vcc
	v_cmp_neq_f32_e32 vcc, -1.0, v0
	s_nop 1
	v_cndmask_b32_e32 v85, v229, v85, vcc
	v_cmp_lt_f32_e64 vcc, |v0|, s56
	s_nop 1
	v_cndmask_b32_e32 v180, v85, v0, vcc
	v_add_f32_e32 v0, v50, v169
	v_mul_f32_e32 v0, 0xbfb8aa3b, v0
	v_exp_f32_e32 v0, v0
	v_add_u32_e32 v50, 0x400, v122
	ds_read2_b32 v[110:111], v50 offset1:32
	ds_read2_b32 v[108:109], v50 offset0:128 offset1:160
	v_add_u32_e32 v50, 0x1000, v122
	v_add_f32_e32 v0, 1.0, v0
	v_rcp_f32_e32 v0, v0
	ds_read2_b32 v[106:107], v50 offset1:32
	ds_read2_b32 v[104:105], v50 offset0:128 offset1:160
	v_add_u32_e32 v50, 0x1400, v122
	ds_read2_b32 v[102:103], v50 offset1:32
	ds_read2_b32 v[100:101], v50 offset0:128 offset1:160
	v_add_u32_e32 v50, 0x2000, v122
	ds_read2_b32 v[98:99], v50 offset1:32
	ds_read2_b32 v[96:97], v50 offset0:128 offset1:160
	v_add_u32_e32 v50, 0x2400, v122
	ds_read2_b32 v[94:95], v50 offset1:32
	ds_read2_b32 v[92:93], v50 offset0:128 offset1:160
	v_add_u32_e32 v50, 0x3000, v122
	v_mul_f32_e32 v0, 0xc1000000, v0
	ds_read2_b32 v[90:91], v50 offset1:32
	ds_read2_b32 v[88:89], v50 offset0:128 offset1:160
	v_add_u32_e32 v50, 0x3400, v122
	v_mul_f32_e32 v85, v0, v180
	v_add_f32_e32 v0, v51, v169
	ds_read2_b32 v[86:87], v50 offset1:32
	ds_read2_b32 v[50:51], v50 offset0:128 offset1:160
	global_load_dword v117, v[116:117], off offset:128
	v_mul_f32_e32 v0, 0xbfb8aa3b, v0
	global_load_dword v116, v[172:173], off offset:128
	global_load_dword v181, v[170:171], off offset:128
	v_exp_f32_e32 v0, v0
	s_nop 0
	v_add_f32_e32 v0, 1.0, v0
	v_rcp_f32_e32 v0, v0
	s_nop 0
	v_mul_f32_e32 v0, 0xc1000000, v0
	v_mul_f32_e32 v0, v0, v180
	v_cndmask_b32_e64 v171, v85, v0, s[38:39]
	s_nop 1
	v_mov_b32_dpp v171, v171 quad_perm:[1,0,3,2] row_mask:0xf bank_mask:0xf
	s_and_saveexec_b64 s[22:23], s[40:41]
	s_xor_b64 s[22:23], exec, s[22:23]
	s_cbranch_execz .LBB0_1193
	v_cvt_pk_bf16_f32 v170, v171, v0
